# LDS-DMA stage rebalance (4+4 per load segment) applied to five GEMM mainloops (GEMM1, GLU/pool, out, up, down)
# baseline (speedup 1.0000x reference)
.LBB0_32:
	s_add_u32 s12, s10, 0x100
	s_addc_u32 s13, s11, 0
	s_add_i32 s33, 0, 0x10000
	s_cmpk_eq_i32 s42, 0x52
	s_cselect_b32 s17, s1, s13
	s_cselect_b32 s16, s0, s12
	s_cselect_b32 s15, s9, s41
	s_cselect_b32 s14, s8, s40
	s_add_i32 s43, 0, 0x14000
	v_add_u32_e32 v142, s33, v207
	v_add_u32_e32 v158, s43, v207
	ds_read_b128 v[130:133], v142
	ds_read_b128 v[134:137], v142 offset:1024
	ds_read_b128 v[138:141], v142 offset:2048
	ds_read_b128 v[142:145], v142 offset:3072
	ds_read_b128 v[146:149], v158
	ds_read_b128 v[150:153], v158 offset:1024
	ds_read_b128 v[154:157], v158 offset:2048
	ds_read_b128 v[158:161], v158 offset:3072
	s_cmp_eq_u32 s42, -2
	s_cbranch_scc1 .Lbal_down_first
	v_lshl_add_u64 v[204:205], v[212:213], 0, s[56:57]
	s_mov_b32 m0, s31
	s_nop 0
	global_load_lds_dwordx4 v[204:205], off
	v_lshl_add_u64 v[204:205], v[214:215], 0, s[56:57]
	s_mov_b32 m0, s34
	s_nop 0
	global_load_lds_dwordx4 v[204:205], off
.Lbal_down_first:
	v_lshl_add_u64 v[204:205], s[10:11], 0, v[180:181]
	s_add_i32 m0, s23, 0xc000
	ds_read_b128 v[162:165], v208
	ds_read_b128 v[166:169], v208 offset:1024
	ds_read_b128 v[170:173], v208 offset:2048
	ds_read_b128 v[184:187], v208 offset:3072
	ds_read_b128 v[188:191], v208 offset:4096
	ds_read_b128 v[192:195], v208 offset:5120
	ds_read_b128 v[196:199], v208 offset:6144
	ds_read_b128 v[200:203], v208 offset:7168
	global_load_lds_dwordx4 v[204:205], off
	v_lshl_add_u64 v[204:205], s[10:11], 0, v[182:183]
	s_add_i32 m0, s23, 0xe000
	s_nop 0
	global_load_lds_dwordx4 v[204:205], off
	s_waitcnt vmcnt(8)
	s_waitcnt lgkmcnt(0)
	s_barrier
	s_setprio 1
	s_waitcnt lgkmcnt(0)
	v_mfma_f32_16x16x32_bf16 v[126:129], v[130:133], v[162:165], v[126:129]
	v_mfma_f32_16x16x32_bf16 v[94:97], v[138:141], v[162:165], v[94:97]
	v_mfma_f32_16x16x32_bf16 v[122:125], v[130:133], v[170:173], v[122:125]
	v_mfma_f32_16x16x32_bf16 v[90:93], v[138:141], v[170:173], v[90:93]
	v_mfma_f32_16x16x32_bf16 v[118:121], v[130:133], v[188:191], v[118:121]
	v_mfma_f32_16x16x32_bf16 v[86:89], v[138:141], v[188:191], v[86:89]
	v_mfma_f32_16x16x32_bf16 v[114:117], v[130:133], v[196:199], v[114:117]
	v_mfma_f32_16x16x32_bf16 v[82:85], v[138:141], v[196:199], v[82:85]
	v_mfma_f32_16x16x32_bf16 v[126:129], v[134:137], v[166:169], v[126:129]
	v_mfma_f32_16x16x32_bf16 v[94:97], v[142:145], v[166:169], v[94:97]
	v_mfma_f32_16x16x32_bf16 v[122:125], v[134:137], v[184:187], v[122:125]
	v_mfma_f32_16x16x32_bf16 v[90:93], v[142:145], v[184:187], v[90:93]
	v_mfma_f32_16x16x32_bf16 v[118:121], v[134:137], v[192:195], v[118:121]
	v_mfma_f32_16x16x32_bf16 v[86:89], v[142:145], v[192:195], v[86:89]
	v_mfma_f32_16x16x32_bf16 v[114:117], v[134:137], v[200:203], v[114:117]
	v_mfma_f32_16x16x32_bf16 v[82:85], v[142:145], v[200:203], v[82:85]
	s_setprio 0
	s_setprio 1
	v_mfma_f32_16x16x32_bf16 v[66:69], v[146:149], v[162:165], v[66:69]
	v_mfma_f32_16x16x32_bf16 v[42:45], v[154:157], v[162:165], v[42:45]
	v_mfma_f32_16x16x32_bf16 v[58:61], v[146:149], v[170:173], v[58:61]
	v_mfma_f32_16x16x32_bf16 v[30:33], v[154:157], v[170:173], v[30:33]
	v_mfma_f32_16x16x32_bf16 v[54:57], v[146:149], v[188:191], v[54:57]
	v_mfma_f32_16x16x32_bf16 v[22:25], v[154:157], v[188:191], v[22:25]
	v_mfma_f32_16x16x32_bf16 v[50:53], v[146:149], v[196:199], v[50:53]
	v_mfma_f32_16x16x32_bf16 v[18:21], v[154:157], v[196:199], v[18:21]
	v_mfma_f32_16x16x32_bf16 v[66:69], v[150:153], v[166:169], v[66:69]
	v_mfma_f32_16x16x32_bf16 v[42:45], v[158:161], v[166:169], v[42:45]
	v_mfma_f32_16x16x32_bf16 v[58:61], v[150:153], v[184:187], v[58:61]
	v_mfma_f32_16x16x32_bf16 v[30:33], v[158:161], v[184:187], v[30:33]
	v_mfma_f32_16x16x32_bf16 v[54:57], v[150:153], v[192:195], v[54:57]
	v_mfma_f32_16x16x32_bf16 v[22:25], v[158:161], v[192:195], v[22:25]
	v_mfma_f32_16x16x32_bf16 v[50:53], v[150:153], v[200:203], v[50:53]
	v_mfma_f32_16x16x32_bf16 v[18:21], v[158:161], v[200:203], v[18:21]
	s_setprio 0
	s_barrier
	s_add_i32 s10, s33, s22
	v_lshl_add_u64 v[204:205], s[14:15], 0, v[178:179]
	s_mov_b32 m0, s10
	ds_read_b128 v[162:165], v208 offset:16384
	ds_read_b128 v[166:169], v208 offset:17408
	ds_read_b128 v[170:173], v208 offset:18432
	ds_read_b128 v[184:187], v208 offset:19456
	ds_read_b128 v[188:191], v208 offset:20480
	ds_read_b128 v[192:195], v208 offset:21504
	ds_read_b128 v[196:199], v208 offset:22528
	ds_read_b128 v[200:203], v208 offset:23552
	global_load_lds_dwordx4 v[204:205], off
	s_add_i32 m0, s10, 0x2000
	s_add_u32 s10, s14, 0x158000
	v_lshl_add_u64 v[210:211], s[14:15], 0, v[176:177]
	s_addc_u32 s11, s15, 0
	s_add_i32 s33, s43, s22
	global_load_lds_dwordx4 v[210:211], off
	v_lshl_add_u64 v[212:213], s[10:11], 0, v[178:179]
	s_mov_b32 m0, s33
	v_lshl_add_u64 v[214:215], s[16:17], 0, v[176:177]
	global_load_lds_dwordx4 v[212:213], off
	v_lshl_add_u64 v[212:213], s[10:11], 0, v[176:177]
	s_add_i32 m0, s33, 0x2000
	s_nop 0
	global_load_lds_dwordx4 v[212:213], off
	v_lshl_add_u64 v[212:213], s[16:17], 0, v[178:179]
	s_waitcnt vmcnt(6)
	s_waitcnt lgkmcnt(0)
	s_barrier
	s_setprio 1
	s_waitcnt lgkmcnt(0)
	v_mfma_f32_16x16x32_bf16 v[110:113], v[130:133], v[162:165], v[110:113]
	v_mfma_f32_16x16x32_bf16 v[78:81], v[138:141], v[162:165], v[78:81]
	v_mfma_f32_16x16x32_bf16 v[106:109], v[130:133], v[170:173], v[106:109]
	v_mfma_f32_16x16x32_bf16 v[74:77], v[138:141], v[170:173], v[74:77]
	v_mfma_f32_16x16x32_bf16 v[102:105], v[130:133], v[188:191], v[102:105]
	v_mfma_f32_16x16x32_bf16 v[70:73], v[138:141], v[188:191], v[70:73]
	v_mfma_f32_16x16x32_bf16 v[98:101], v[130:133], v[196:199], v[98:101]
	v_mfma_f32_16x16x32_bf16 v[62:65], v[138:141], v[196:199], v[62:65]
	v_mfma_f32_16x16x32_bf16 v[110:113], v[134:137], v[166:169], v[110:113]
	v_mfma_f32_16x16x32_bf16 v[78:81], v[142:145], v[166:169], v[78:81]
	v_mfma_f32_16x16x32_bf16 v[106:109], v[134:137], v[184:187], v[106:109]
	v_mfma_f32_16x16x32_bf16 v[74:77], v[142:145], v[184:187], v[74:77]
	v_mfma_f32_16x16x32_bf16 v[102:105], v[134:137], v[192:195], v[102:105]
	v_mfma_f32_16x16x32_bf16 v[70:73], v[142:145], v[192:195], v[70:73]
	v_mfma_f32_16x16x32_bf16 v[98:101], v[134:137], v[200:203], v[98:101]
	v_mfma_f32_16x16x32_bf16 v[62:65], v[142:145], v[200:203], v[62:65]
	s_setprio 0
	s_setprio 1
	v_mfma_f32_16x16x32_bf16 v[46:49], v[146:149], v[162:165], v[46:49]
	v_mfma_f32_16x16x32_bf16 v[12:15], v[154:157], v[162:165], v[12:15]
	v_mfma_f32_16x16x32_bf16 v[38:41], v[146:149], v[170:173], v[38:41]
	v_mfma_f32_16x16x32_bf16 v[8:11], v[154:157], v[170:173], v[8:11]
	v_mfma_f32_16x16x32_bf16 v[34:37], v[146:149], v[188:191], v[34:37]
	v_mfma_f32_16x16x32_bf16 v[4:7], v[154:157], v[188:191], v[4:7]
	v_mfma_f32_16x16x32_bf16 v[26:29], v[146:149], v[196:199], v[26:29]
	v_mfma_f32_16x16x32_bf16 v[0:3], v[154:157], v[196:199], v[0:3]
	v_mfma_f32_16x16x32_bf16 v[46:49], v[150:153], v[166:169], v[46:49]
	v_mfma_f32_16x16x32_bf16 v[12:15], v[158:161], v[166:169], v[12:15]
	v_mfma_f32_16x16x32_bf16 v[38:41], v[150:153], v[184:187], v[38:41]
	v_mfma_f32_16x16x32_bf16 v[8:11], v[158:161], v[184:187], v[8:11]
	v_mfma_f32_16x16x32_bf16 v[34:37], v[150:153], v[192:195], v[34:37]
	v_mfma_f32_16x16x32_bf16 v[4:7], v[158:161], v[192:195], v[4:7]
	v_mfma_f32_16x16x32_bf16 v[26:29], v[150:153], v[200:203], v[26:29]
	v_mfma_f32_16x16x32_bf16 v[0:3], v[158:161], v[200:203], v[0:3]
	s_setprio 0
	s_barrier
	s_add_i32 s33, 0, 0x18000
	s_add_i32 s43, 0, 0x1c000
	v_add_u32_e32 v142, s33, v207
	v_add_u32_e32 v158, s43, v207
	ds_read_b128 v[130:133], v142
	ds_read_b128 v[134:137], v142 offset:1024
	ds_read_b128 v[138:141], v142 offset:2048
	ds_read_b128 v[142:145], v142 offset:3072
	ds_read_b128 v[146:149], v158
	ds_read_b128 v[150:153], v158 offset:1024
	ds_read_b128 v[154:157], v158 offset:2048
	ds_read_b128 v[158:161], v158 offset:3072
	s_add_u32 s10, s16, 0x158000
	s_addc_u32 s11, s17, 0
	s_mov_b32 m0, s23
	s_nop 0
	global_load_lds_dwordx4 v[212:213], off
	s_mov_b32 m0, s24
	s_nop 0
	global_load_lds_dwordx4 v[214:215], off
	s_mov_b32 m0, s25
	v_lshl_add_u64 v[222:223], s[10:11], 0, v[178:179]
	ds_read_b128 v[162:165], v208 offset:32768
	ds_read_b128 v[166:169], v208 offset:33792
	ds_read_b128 v[170:173], v208 offset:34816
	ds_read_b128 v[184:187], v208 offset:35840
	ds_read_b128 v[188:191], v208 offset:36864
	ds_read_b128 v[192:195], v208 offset:37888
	ds_read_b128 v[196:199], v208 offset:38912
	ds_read_b128 v[200:203], v208 offset:39936
	global_load_lds_dwordx4 v[222:223], off
	v_lshl_add_u64 v[222:223], s[10:11], 0, v[176:177]
	s_mov_b32 m0, s26
	s_nop 0
	global_load_lds_dwordx4 v[222:223], off
	s_waitcnt vmcnt(8)
	s_waitcnt lgkmcnt(0)
	s_barrier
	s_setprio 1
	s_waitcnt lgkmcnt(0)
	v_mfma_f32_16x16x32_bf16 v[126:129], v[130:133], v[162:165], v[126:129]
	v_mfma_f32_16x16x32_bf16 v[94:97], v[138:141], v[162:165], v[94:97]
	v_mfma_f32_16x16x32_bf16 v[122:125], v[130:133], v[170:173], v[122:125]
	v_mfma_f32_16x16x32_bf16 v[90:93], v[138:141], v[170:173], v[90:93]
	v_mfma_f32_16x16x32_bf16 v[118:121], v[130:133], v[188:191], v[118:121]
	v_mfma_f32_16x16x32_bf16 v[86:89], v[138:141], v[188:191], v[86:89]
	v_mfma_f32_16x16x32_bf16 v[114:117], v[130:133], v[196:199], v[114:117]
	v_mfma_f32_16x16x32_bf16 v[82:85], v[138:141], v[196:199], v[82:85]
	v_mfma_f32_16x16x32_bf16 v[126:129], v[134:137], v[166:169], v[126:129]
	v_mfma_f32_16x16x32_bf16 v[94:97], v[142:145], v[166:169], v[94:97]
	v_mfma_f32_16x16x32_bf16 v[122:125], v[134:137], v[184:187], v[122:125]
	v_mfma_f32_16x16x32_bf16 v[90:93], v[142:145], v[184:187], v[90:93]
	v_mfma_f32_16x16x32_bf16 v[118:121], v[134:137], v[192:195], v[118:121]
	v_mfma_f32_16x16x32_bf16 v[86:89], v[142:145], v[192:195], v[86:89]
	v_mfma_f32_16x16x32_bf16 v[114:117], v[134:137], v[200:203], v[114:117]
	v_mfma_f32_16x16x32_bf16 v[82:85], v[142:145], v[200:203], v[82:85]
	s_setprio 0
	s_setprio 1
	v_mfma_f32_16x16x32_bf16 v[66:69], v[146:149], v[162:165], v[66:69]
	v_mfma_f32_16x16x32_bf16 v[42:45], v[154:157], v[162:165], v[42:45]
	v_mfma_f32_16x16x32_bf16 v[58:61], v[146:149], v[170:173], v[58:61]
	v_mfma_f32_16x16x32_bf16 v[30:33], v[154:157], v[170:173], v[30:33]
	v_mfma_f32_16x16x32_bf16 v[54:57], v[146:149], v[188:191], v[54:57]
	v_mfma_f32_16x16x32_bf16 v[22:25], v[154:157], v[188:191], v[22:25]
	v_mfma_f32_16x16x32_bf16 v[50:53], v[146:149], v[196:199], v[50:53]
	v_mfma_f32_16x16x32_bf16 v[18:21], v[154:157], v[196:199], v[18:21]
	v_mfma_f32_16x16x32_bf16 v[66:69], v[150:153], v[166:169], v[66:69]
	v_mfma_f32_16x16x32_bf16 v[42:45], v[158:161], v[166:169], v[42:45]
	v_mfma_f32_16x16x32_bf16 v[58:61], v[150:153], v[184:187], v[58:61]
	v_mfma_f32_16x16x32_bf16 v[30:33], v[158:161], v[184:187], v[30:33]
	v_mfma_f32_16x16x32_bf16 v[54:57], v[150:153], v[192:195], v[54:57]
	v_mfma_f32_16x16x32_bf16 v[22:25], v[158:161], v[192:195], v[22:25]
	v_mfma_f32_16x16x32_bf16 v[50:53], v[150:153], v[200:203], v[50:53]
	v_mfma_f32_16x16x32_bf16 v[18:21], v[158:161], v[200:203], v[18:21]
	s_setprio 0
	s_barrier
	s_add_i32 s10, s33, s22
	v_lshl_add_u64 v[204:205], v[204:205], 0, s[56:57]
	s_mov_b32 m0, s10
	ds_read_b128 v[162:165], v208 offset:49152
	ds_read_b128 v[166:169], v208 offset:50176
	ds_read_b128 v[170:173], v208 offset:51200
	ds_read_b128 v[184:187], v208 offset:52224
	ds_read_b128 v[188:191], v208 offset:53248
	ds_read_b128 v[192:195], v208 offset:54272
	ds_read_b128 v[196:199], v208 offset:55296
	ds_read_b128 v[200:203], v208 offset:56320
	global_load_lds_dwordx4 v[204:205], off
	s_add_i32 m0, s10, 0x2000
	s_add_u32 s10, s14, 0x158080
	v_lshl_add_u64 v[204:205], v[210:211], 0, s[56:57]
	s_addc_u32 s11, s15, 0
	s_add_i32 s14, s43, s22
	global_load_lds_dwordx4 v[204:205], off
	v_lshl_add_u64 v[204:205], s[10:11], 0, v[178:179]
	s_mov_b32 m0, s14
	s_nop 0
	global_load_lds_dwordx4 v[204:205], off
	v_lshl_add_u64 v[204:205], s[10:11], 0, v[176:177]
	s_add_i32 m0, s14, 0x2000
	s_nop 0
	global_load_lds_dwordx4 v[204:205], off
	s_cmpk_eq_i32 s42, 0x52
	s_cbranch_scc0 .Lbal_down_notlast
	v_lshl_add_u64 v[204:205], v[212:213], 0, s[56:57]
	s_mov_b32 m0, s31
	s_nop 0
	global_load_lds_dwordx4 v[204:205], off
	v_lshl_add_u64 v[204:205], v[214:215], 0, s[56:57]
	s_mov_b32 m0, s34
	s_nop 0
	global_load_lds_dwordx4 v[204:205], off
	s_waitcnt vmcnt(8)
	s_branch .Lbal_down_join

.Lbal_down_join:
	s_waitcnt lgkmcnt(0)
	s_barrier
	s_setprio 1
	s_waitcnt lgkmcnt(0)
	v_mfma_f32_16x16x32_bf16 v[110:113], v[130:133], v[162:165], v[110:113]
	v_mfma_f32_16x16x32_bf16 v[78:81], v[138:141], v[162:165], v[78:81]
	v_mfma_f32_16x16x32_bf16 v[106:109], v[130:133], v[170:173], v[106:109]
	v_mfma_f32_16x16x32_bf16 v[74:77], v[138:141], v[170:173], v[74:77]
	v_mfma_f32_16x16x32_bf16 v[102:105], v[130:133], v[188:191], v[102:105]
	v_mfma_f32_16x16x32_bf16 v[70:73], v[138:141], v[188:191], v[70:73]
	v_mfma_f32_16x16x32_bf16 v[98:101], v[130:133], v[196:199], v[98:101]
	v_mfma_f32_16x16x32_bf16 v[62:65], v[138:141], v[196:199], v[62:65]
	v_mfma_f32_16x16x32_bf16 v[110:113], v[134:137], v[166:169], v[110:113]
	v_mfma_f32_16x16x32_bf16 v[78:81], v[142:145], v[166:169], v[78:81]
	v_mfma_f32_16x16x32_bf16 v[106:109], v[134:137], v[184:187], v[106:109]
	v_mfma_f32_16x16x32_bf16 v[74:77], v[142:145], v[184:187], v[74:77]
	v_mfma_f32_16x16x32_bf16 v[102:105], v[134:137], v[192:195], v[102:105]
	v_mfma_f32_16x16x32_bf16 v[70:73], v[142:145], v[192:195], v[70:73]
	v_mfma_f32_16x16x32_bf16 v[98:101], v[134:137], v[200:203], v[98:101]
	v_mfma_f32_16x16x32_bf16 v[62:65], v[142:145], v[200:203], v[62:65]
	s_setprio 0
	s_setprio 1
	v_mfma_f32_16x16x32_bf16 v[46:49], v[146:149], v[162:165], v[46:49]
	v_mfma_f32_16x16x32_bf16 v[12:15], v[154:157], v[162:165], v[12:15]
	v_mfma_f32_16x16x32_bf16 v[38:41], v[146:149], v[170:173], v[38:41]
	v_mfma_f32_16x16x32_bf16 v[8:11], v[154:157], v[170:173], v[8:11]
	v_mfma_f32_16x16x32_bf16 v[34:37], v[146:149], v[188:191], v[34:37]
	v_mfma_f32_16x16x32_bf16 v[4:7], v[154:157], v[188:191], v[4:7]
	v_mfma_f32_16x16x32_bf16 v[26:29], v[146:149], v[196:199], v[26:29]
	v_mfma_f32_16x16x32_bf16 v[0:3], v[154:157], v[196:199], v[0:3]
	v_mfma_f32_16x16x32_bf16 v[46:49], v[150:153], v[166:169], v[46:49]
	v_mfma_f32_16x16x32_bf16 v[12:15], v[158:161], v[166:169], v[12:15]
	v_mfma_f32_16x16x32_bf16 v[38:41], v[150:153], v[184:187], v[38:41]
	v_mfma_f32_16x16x32_bf16 v[8:11], v[158:161], v[184:187], v[8:11]
	v_mfma_f32_16x16x32_bf16 v[34:37], v[150:153], v[192:195], v[34:37]
	v_mfma_f32_16x16x32_bf16 v[4:7], v[158:161], v[192:195], v[4:7]
	v_mfma_f32_16x16x32_bf16 v[26:29], v[150:153], v[200:203], v[26:29]
	v_mfma_f32_16x16x32_bf16 v[0:3], v[158:161], v[200:203], v[0:3]
	s_setprio 0
	s_barrier
	s_add_i32 s42, s42, 2
	s_add_u32 s40, s40, 0x100
	s_addc_u32 s41, s41, 0
	s_cmpk_gt_u32 s42, 0x53
	s_mov_b64 s[10:11], s[12:13]
	s_cbranch_scc0 .LBB0_32
	s_and_b64 vcc, exec, s[6:7]
	s_cbranch_vccz .LBB0_35
	s_barrier

.Lbal_up_first:
	v_lshl_add_u64 v[214:215], s[6:7], 0, v[180:181]
	s_add_i32 m0, s41, 0xc000
	ds_read_b128 v[170:173], v192
	ds_read_b128 v[184:187], v192 offset:1024
	ds_read_b128 v[194:197], v192 offset:2048
	ds_read_b128 v[198:201], v192 offset:3072
	ds_read_b128 v[202:205], v192 offset:4096
	ds_read_b128 v[206:209], v192 offset:5120
	ds_read_b128 v[210:213], v192 offset:6144
	ds_read_b128 v[222:225], v192 offset:7168
	global_load_lds_dwordx4 v[214:215], off
	v_lshl_add_u64 v[214:215], s[6:7], 0, v[182:183]
	s_add_i32 m0, s41, 0xe000
	s_nop 0
	global_load_lds_dwordx4 v[214:215], off
	s_waitcnt vmcnt(8)
	s_waitcnt lgkmcnt(0)
	s_barrier
	s_setprio 1
	s_waitcnt lgkmcnt(0)
	v_mfma_f32_16x16x32_bf16 v[150:153], v[54:57], v[170:173], v[150:153]
	v_mfma_f32_16x16x32_bf16 v[142:145], v[66:69], v[170:173], v[142:145]
	v_mfma_f32_16x16x32_bf16 v[134:137], v[54:57], v[194:197], v[134:137]
	v_mfma_f32_16x16x32_bf16 v[126:129], v[66:69], v[194:197], v[126:129]
	v_mfma_f32_16x16x32_bf16 v[118:121], v[54:57], v[202:205], v[118:121]
	v_mfma_f32_16x16x32_bf16 v[114:117], v[66:69], v[202:205], v[114:117]
	v_mfma_f32_16x16x32_bf16 v[110:113], v[54:57], v[210:213], v[110:113]
	v_mfma_f32_16x16x32_bf16 v[106:109], v[66:69], v[210:213], v[106:109]
	v_mfma_f32_16x16x32_bf16 v[150:153], v[62:65], v[184:187], v[150:153]
	v_mfma_f32_16x16x32_bf16 v[142:145], v[70:73], v[184:187], v[142:145]
	v_mfma_f32_16x16x32_bf16 v[134:137], v[62:65], v[198:201], v[134:137]
	v_mfma_f32_16x16x32_bf16 v[126:129], v[70:73], v[198:201], v[126:129]
	v_mfma_f32_16x16x32_bf16 v[118:121], v[62:65], v[206:209], v[118:121]
	v_mfma_f32_16x16x32_bf16 v[114:117], v[70:73], v[206:209], v[114:117]
	v_mfma_f32_16x16x32_bf16 v[110:113], v[62:65], v[222:225], v[110:113]
	v_mfma_f32_16x16x32_bf16 v[106:109], v[70:73], v[222:225], v[106:109]
	s_setprio 0
	s_setprio 1
	v_mfma_f32_16x16x32_bf16 v[158:161], v[74:77], v[170:173], v[158:161]
	v_mfma_f32_16x16x32_bf16 v[154:157], v[82:85], v[170:173], v[154:157]
	v_mfma_f32_16x16x32_bf16 v[146:149], v[74:77], v[194:197], v[146:149]
	v_mfma_f32_16x16x32_bf16 v[138:141], v[82:85], v[194:197], v[138:141]
	v_mfma_f32_16x16x32_bf16 v[130:133], v[74:77], v[202:205], v[130:133]
	v_mfma_f32_16x16x32_bf16 v[122:125], v[82:85], v[202:205], v[122:125]
	v_mfma_f32_16x16x32_bf16 v[102:105], v[74:77], v[210:213], v[102:105]
	v_mfma_f32_16x16x32_bf16 v[98:101], v[82:85], v[210:213], v[98:101]
	v_mfma_f32_16x16x32_bf16 v[158:161], v[78:81], v[184:187], v[158:161]
	v_mfma_f32_16x16x32_bf16 v[154:157], v[86:89], v[184:187], v[154:157]
	v_mfma_f32_16x16x32_bf16 v[146:149], v[78:81], v[198:201], v[146:149]
	v_mfma_f32_16x16x32_bf16 v[138:141], v[86:89], v[198:201], v[138:141]
	v_mfma_f32_16x16x32_bf16 v[130:133], v[78:81], v[206:209], v[130:133]
	v_mfma_f32_16x16x32_bf16 v[122:125], v[86:89], v[206:209], v[122:125]
	v_mfma_f32_16x16x32_bf16 v[102:105], v[78:81], v[222:225], v[102:105]
	v_mfma_f32_16x16x32_bf16 v[98:101], v[86:89], v[222:225], v[98:101]
	s_setprio 0
	s_barrier
	s_add_i32 s33, s33, s38
	v_lshl_add_u64 v[214:215], s[8:9], 0, v[166:167]
	s_mov_b32 m0, s33
	ds_read_b128 v[170:173], v192 offset:16384
	ds_read_b128 v[184:187], v192 offset:17408
	ds_read_b128 v[194:197], v192 offset:18432
	ds_read_b128 v[198:201], v192 offset:19456
	ds_read_b128 v[202:205], v192 offset:20480
	ds_read_b128 v[206:209], v192 offset:21504
	ds_read_b128 v[210:213], v192 offset:22528
	ds_read_b128 v[222:225], v192 offset:23552
	global_load_lds_dwordx4 v[214:215], off
	s_add_i32 m0, s33, 0x2000
	s_add_u32 s52, s8, 0x80000
	v_lshl_add_u64 v[234:235], s[8:9], 0, v[162:163]
	s_addc_u32 s53, s9, 0
	s_add_i32 s33, s54, s38
	global_load_lds_dwordx4 v[234:235], off
	v_lshl_add_u64 v[230:231], s[52:53], 0, v[166:167]
	s_mov_b32 m0, s33
	v_lshl_add_u64 v[236:237], s[10:11], 0, v[168:169]
	global_load_lds_dwordx4 v[230:231], off
	v_lshl_add_u64 v[230:231], s[52:53], 0, v[162:163]
	s_add_i32 m0, s33, 0x2000
	v_lshl_add_u64 v[238:239], s[10:11], 0, v[164:165]
	global_load_lds_dwordx4 v[230:231], off
	s_waitcnt vmcnt(6)
	s_waitcnt lgkmcnt(0)
	s_barrier
	s_setprio 1
	s_waitcnt lgkmcnt(0)
	v_mfma_f32_16x16x32_bf16 v[58:61], v[54:57], v[170:173], v[58:61]
	v_mfma_f32_16x16x32_bf16 v[46:49], v[66:69], v[170:173], v[46:49]
	v_mfma_f32_16x16x32_bf16 v[38:41], v[54:57], v[194:197], v[38:41]
	v_mfma_f32_16x16x32_bf16 v[30:33], v[66:69], v[194:197], v[30:33]
	v_mfma_f32_16x16x32_bf16 v[22:25], v[54:57], v[202:205], v[22:25]
	v_mfma_f32_16x16x32_bf16 v[18:21], v[66:69], v[202:205], v[18:21]
	v_mfma_f32_16x16x32_bf16 v[8:11], v[54:57], v[210:213], v[8:11]
	v_mfma_f32_16x16x32_bf16 v[12:15], v[66:69], v[210:213], v[12:15]
	v_mfma_f32_16x16x32_bf16 v[58:61], v[62:65], v[184:187], v[58:61]
	v_mfma_f32_16x16x32_bf16 v[46:49], v[70:73], v[184:187], v[46:49]
	v_mfma_f32_16x16x32_bf16 v[38:41], v[62:65], v[198:201], v[38:41]
	v_mfma_f32_16x16x32_bf16 v[30:33], v[70:73], v[198:201], v[30:33]
	v_mfma_f32_16x16x32_bf16 v[22:25], v[62:65], v[206:209], v[22:25]
	v_mfma_f32_16x16x32_bf16 v[18:21], v[70:73], v[206:209], v[18:21]
	v_mfma_f32_16x16x32_bf16 v[8:11], v[62:65], v[222:225], v[8:11]
	v_mfma_f32_16x16x32_bf16 v[12:15], v[70:73], v[222:225], v[12:15]
	s_setprio 0
	s_setprio 1
	v_mfma_f32_16x16x32_bf16 v[50:53], v[74:77], v[194:197], v[50:53]
	v_mfma_f32_16x16x32_bf16 v[42:45], v[82:85], v[194:197], v[42:45]
	v_mfma_f32_16x16x32_bf16 v[34:37], v[74:77], v[202:205], v[34:37]
	v_mfma_f32_16x16x32_bf16 v[26:29], v[82:85], v[202:205], v[26:29]
	v_mfma_f32_16x16x32_bf16 v[0:3], v[74:77], v[210:213], v[0:3]
	v_mfma_f32_16x16x32_bf16 v[4:7], v[82:85], v[210:213], v[4:7]
	v_mfma_f32_16x16x32_bf16 v[54:57], v[74:77], v[170:173], v[94:97]
	v_mfma_f32_16x16x32_bf16 v[62:65], v[82:85], v[170:173], v[90:93]
	v_mfma_f32_16x16x32_bf16 v[50:53], v[78:81], v[198:201], v[50:53]
	v_mfma_f32_16x16x32_bf16 v[42:45], v[86:89], v[198:201], v[42:45]
	v_mfma_f32_16x16x32_bf16 v[34:37], v[78:81], v[206:209], v[34:37]
	v_mfma_f32_16x16x32_bf16 v[26:29], v[86:89], v[206:209], v[26:29]
	v_mfma_f32_16x16x32_bf16 v[0:3], v[78:81], v[222:225], v[0:3]
	v_mfma_f32_16x16x32_bf16 v[4:7], v[86:89], v[222:225], v[4:7]
	v_mfma_f32_16x16x32_bf16 v[54:57], v[78:81], v[184:187], v[54:57]
	v_mfma_f32_16x16x32_bf16 v[62:65], v[86:89], v[184:187], v[62:65]
	s_setprio 0
	s_barrier
	s_add_i32 s33, 0, 0x18000
	v_add_u32_e32 v16, s33, v190
	s_add_i32 s52, 0, 0x1c000
	ds_read_b128 v[66:69], v16
	ds_read_b128 v[70:73], v16 offset:1024
	ds_read_b128 v[74:77], v16 offset:2048
	ds_read_b128 v[78:81], v16 offset:3072
	v_add_u32_e32 v16, s52, v190
	ds_read_b128 v[82:85], v16
	ds_read_b128 v[86:89], v16 offset:1024
	ds_read_b128 v[170:173], v16 offset:2048
	ds_read_b128 v[184:187], v16 offset:3072
	s_add_u32 s10, s10, 0x80000
	s_addc_u32 s11, s11, 0
	s_mov_b32 m0, s41
	s_nop 0
	global_load_lds_dwordx4 v[236:237], off
	s_mov_b32 m0, s42
	s_nop 0
	global_load_lds_dwordx4 v[238:239], off
	s_mov_b32 m0, s43
	v_lshl_add_u64 v[230:231], s[10:11], 0, v[168:169]
	ds_read_b128 v[90:93], v192 offset:32768
	ds_read_b128 v[94:97], v192 offset:33792
	ds_read_b128 v[194:197], v192 offset:34816
	ds_read_b128 v[198:201], v192 offset:35840
	ds_read_b128 v[202:205], v192 offset:36864
	ds_read_b128 v[206:209], v192 offset:37888
	ds_read_b128 v[210:213], v192 offset:38912
	ds_read_b128 v[222:225], v192 offset:39936
	global_load_lds_dwordx4 v[230:231], off
	v_lshl_add_u64 v[230:231], s[10:11], 0, v[164:165]
	s_mov_b32 m0, s44
	s_nop 0
	global_load_lds_dwordx4 v[230:231], off
	s_waitcnt vmcnt(8)
	s_waitcnt lgkmcnt(0)
	s_barrier
	s_setprio 1
	s_waitcnt lgkmcnt(0)
	v_mfma_f32_16x16x32_bf16 v[150:153], v[66:69], v[90:93], v[150:153]
	v_mfma_f32_16x16x32_bf16 v[142:145], v[74:77], v[90:93], v[142:145]
	v_mfma_f32_16x16x32_bf16 v[134:137], v[66:69], v[194:197], v[134:137]
	v_mfma_f32_16x16x32_bf16 v[126:129], v[74:77], v[194:197], v[126:129]
	v_mfma_f32_16x16x32_bf16 v[118:121], v[66:69], v[202:205], v[118:121]
	v_mfma_f32_16x16x32_bf16 v[114:117], v[74:77], v[202:205], v[114:117]
	v_mfma_f32_16x16x32_bf16 v[110:113], v[66:69], v[210:213], v[110:113]
	v_mfma_f32_16x16x32_bf16 v[106:109], v[74:77], v[210:213], v[106:109]
	v_mfma_f32_16x16x32_bf16 v[150:153], v[70:73], v[94:97], v[150:153]
	v_mfma_f32_16x16x32_bf16 v[142:145], v[78:81], v[94:97], v[142:145]
	v_mfma_f32_16x16x32_bf16 v[134:137], v[70:73], v[198:201], v[134:137]
	v_mfma_f32_16x16x32_bf16 v[126:129], v[78:81], v[198:201], v[126:129]
	v_mfma_f32_16x16x32_bf16 v[118:121], v[70:73], v[206:209], v[118:121]
	v_mfma_f32_16x16x32_bf16 v[114:117], v[78:81], v[206:209], v[114:117]
	v_mfma_f32_16x16x32_bf16 v[110:113], v[70:73], v[222:225], v[110:113]
	v_mfma_f32_16x16x32_bf16 v[106:109], v[78:81], v[222:225], v[106:109]
	s_setprio 0
	s_setprio 1
	v_mfma_f32_16x16x32_bf16 v[158:161], v[82:85], v[90:93], v[158:161]
	v_mfma_f32_16x16x32_bf16 v[90:93], v[170:173], v[90:93], v[154:157]
	v_mfma_f32_16x16x32_bf16 v[154:157], v[184:187], v[94:97], v[90:93]
	v_mfma_f32_16x16x32_bf16 v[90:93], v[82:85], v[194:197], v[146:149]
	v_mfma_f32_16x16x32_bf16 v[146:149], v[86:89], v[198:201], v[90:93]
	v_mfma_f32_16x16x32_bf16 v[90:93], v[170:173], v[194:197], v[138:141]
	v_mfma_f32_16x16x32_bf16 v[138:141], v[184:187], v[198:201], v[90:93]
	v_mfma_f32_16x16x32_bf16 v[90:93], v[82:85], v[202:205], v[130:133]
	v_mfma_f32_16x16x32_bf16 v[130:133], v[86:89], v[206:209], v[90:93]
	v_mfma_f32_16x16x32_bf16 v[90:93], v[170:173], v[202:205], v[122:125]
	v_mfma_f32_16x16x32_bf16 v[122:125], v[184:187], v[206:209], v[90:93]
	v_mfma_f32_16x16x32_bf16 v[90:93], v[82:85], v[210:213], v[102:105]
	v_mfma_f32_16x16x32_bf16 v[102:105], v[86:89], v[222:225], v[90:93]
	v_mfma_f32_16x16x32_bf16 v[90:93], v[170:173], v[210:213], v[98:101]
	v_mfma_f32_16x16x32_bf16 v[158:161], v[86:89], v[94:97], v[158:161]
	v_mfma_f32_16x16x32_bf16 v[98:101], v[184:187], v[222:225], v[90:93]
	s_setprio 0
	s_barrier
	s_add_i32 s10, s33, s38
	v_lshl_add_u64 v[94:95], v[214:215], 0, s[56:57]
	s_mov_b32 m0, s10
	s_nop 0
	ds_read_b128 v[90:93], v192 offset:49152
	ds_read_b128 v[194:197], v192 offset:50176
	ds_read_b128 v[198:201], v192 offset:51200
	ds_read_b128 v[202:205], v192 offset:52224
	ds_read_b128 v[206:209], v192 offset:53248
	ds_read_b128 v[210:213], v192 offset:54272
	ds_read_b128 v[222:225], v192 offset:55296
	ds_read_b128 v[230:233], v192 offset:56320
	global_load_lds_dwordx4 v[94:95], off
	s_add_i32 m0, s10, 0x2000
	s_add_u32 s8, s8, 0x80080
	v_lshl_add_u64 v[94:95], v[234:235], 0, s[56:57]
	s_addc_u32 s9, s9, 0
	s_add_i32 s10, s52, s38
	global_load_lds_dwordx4 v[94:95], off
	v_lshl_add_u64 v[94:95], s[8:9], 0, v[166:167]
	s_mov_b32 m0, s10
	s_nop 0
	global_load_lds_dwordx4 v[94:95], off
	v_lshl_add_u64 v[94:95], s[8:9], 0, v[162:163]
	s_add_i32 m0, s10, 0x2000
	s_nop 0
	global_load_lds_dwordx4 v[94:95], off
	s_cmp_eq_u32 s51, 28
	s_cbranch_scc0 .Lbal_up_notlast
	v_lshl_add_u64 v[94:95], v[236:237], 0, s[56:57]
	s_mov_b32 m0, s46
	s_nop 0
	global_load_lds_dwordx4 v[94:95], off
	v_lshl_add_u64 v[94:95], v[238:239], 0, s[56:57]
	s_mov_b32 m0, s47
	s_nop 0
	global_load_lds_dwordx4 v[94:95], off
	s_waitcnt vmcnt(8)
	s_branch .Lbal_up_join

.LBB0_108:
	s_add_u32 s16, s14, 0xfff80080
	s_addc_u32 s17, s15, -1
	s_add_i32 s33, 0, 0x10000
	s_cmp_eq_u32 s44, 28
	s_cselect_b32 s19, s9, s17
	s_cselect_b32 s18, s40, s16
	s_cselect_b32 s17, s7, s43
	s_cselect_b32 s16, s41, s42
	s_add_i32 s45, 0, 0x14000
	v_add_u32_e32 v142, s33, v207
	v_add_u32_e32 v158, s45, v207
	ds_read_b128 v[130:133], v142
	ds_read_b128 v[134:137], v142 offset:1024
	ds_read_b128 v[138:141], v142 offset:2048
	ds_read_b128 v[142:145], v142 offset:3072
	ds_read_b128 v[146:149], v158
	ds_read_b128 v[150:153], v158 offset:1024
	ds_read_b128 v[154:157], v158 offset:2048
	ds_read_b128 v[158:161], v158 offset:3072
	s_cmp_eq_u32 s44, -2
	s_cbranch_scc1 .Lbal_out_first
	v_lshl_add_u64 v[170:171], v[204:205], 0, s[56:57]
	s_mov_b32 m0, s35
	s_nop 0
	global_load_lds_dwordx4 v[170:171], off
	v_lshl_add_u64 v[170:171], v[214:215], 0, s[56:57]
	s_mov_b32 m0, s36
	s_nop 0
	global_load_lds_dwordx4 v[170:171], off
.Lbal_out_first:
	v_lshl_add_u64 v[170:171], s[14:15], 0, v[180:181]
	s_add_i32 m0, s25, 0xc000
	ds_read_b128 v[162:165], v208
	ds_read_b128 v[166:169], v208 offset:1024
	ds_read_b128 v[184:187], v208 offset:2048
	ds_read_b128 v[188:191], v208 offset:3072
	ds_read_b128 v[192:195], v208 offset:4096
	ds_read_b128 v[196:199], v208 offset:5120
	ds_read_b128 v[200:203], v208 offset:6144
	ds_read_b128 v[210:213], v208 offset:7168
	global_load_lds_dwordx4 v[170:171], off
	v_lshl_add_u64 v[170:171], s[14:15], 0, v[182:183]
	s_add_i32 m0, s25, 0xe000
	s_nop 0
	global_load_lds_dwordx4 v[170:171], off
	s_waitcnt vmcnt(8)
	s_waitcnt lgkmcnt(0)
	s_barrier
	s_setprio 1
	s_waitcnt lgkmcnt(0)
	v_mfma_f32_16x16x32_bf16 v[126:129], v[130:133], v[162:165], v[126:129]
	v_mfma_f32_16x16x32_bf16 v[94:97], v[138:141], v[162:165], v[94:97]
	v_mfma_f32_16x16x32_bf16 v[122:125], v[130:133], v[184:187], v[122:125]
	v_mfma_f32_16x16x32_bf16 v[90:93], v[138:141], v[184:187], v[90:93]
	v_mfma_f32_16x16x32_bf16 v[118:121], v[130:133], v[192:195], v[118:121]
	v_mfma_f32_16x16x32_bf16 v[86:89], v[138:141], v[192:195], v[86:89]
	v_mfma_f32_16x16x32_bf16 v[114:117], v[130:133], v[200:203], v[114:117]
	v_mfma_f32_16x16x32_bf16 v[82:85], v[138:141], v[200:203], v[82:85]
	v_mfma_f32_16x16x32_bf16 v[126:129], v[134:137], v[166:169], v[126:129]
	v_mfma_f32_16x16x32_bf16 v[94:97], v[142:145], v[166:169], v[94:97]
	v_mfma_f32_16x16x32_bf16 v[122:125], v[134:137], v[188:191], v[122:125]
	v_mfma_f32_16x16x32_bf16 v[90:93], v[142:145], v[188:191], v[90:93]
	v_mfma_f32_16x16x32_bf16 v[118:121], v[134:137], v[196:199], v[118:121]
	v_mfma_f32_16x16x32_bf16 v[86:89], v[142:145], v[196:199], v[86:89]
	v_mfma_f32_16x16x32_bf16 v[114:117], v[134:137], v[210:213], v[114:117]
	v_mfma_f32_16x16x32_bf16 v[82:85], v[142:145], v[210:213], v[82:85]
	s_setprio 0
	s_setprio 1
	v_mfma_f32_16x16x32_bf16 v[66:69], v[146:149], v[162:165], v[66:69]
	v_mfma_f32_16x16x32_bf16 v[42:45], v[154:157], v[162:165], v[42:45]
	v_mfma_f32_16x16x32_bf16 v[58:61], v[146:149], v[184:187], v[58:61]
	v_mfma_f32_16x16x32_bf16 v[30:33], v[154:157], v[184:187], v[30:33]
	v_mfma_f32_16x16x32_bf16 v[54:57], v[146:149], v[192:195], v[54:57]
	v_mfma_f32_16x16x32_bf16 v[22:25], v[154:157], v[192:195], v[22:25]
	v_mfma_f32_16x16x32_bf16 v[50:53], v[146:149], v[200:203], v[50:53]
	v_mfma_f32_16x16x32_bf16 v[18:21], v[154:157], v[200:203], v[18:21]
	v_mfma_f32_16x16x32_bf16 v[66:69], v[150:153], v[166:169], v[66:69]
	v_mfma_f32_16x16x32_bf16 v[42:45], v[158:161], v[166:169], v[42:45]
	v_mfma_f32_16x16x32_bf16 v[58:61], v[150:153], v[188:191], v[58:61]
	v_mfma_f32_16x16x32_bf16 v[30:33], v[158:161], v[188:191], v[30:33]
	v_mfma_f32_16x16x32_bf16 v[54:57], v[150:153], v[196:199], v[54:57]
	v_mfma_f32_16x16x32_bf16 v[22:25], v[158:161], v[196:199], v[22:25]
	v_mfma_f32_16x16x32_bf16 v[50:53], v[150:153], v[210:213], v[50:53]
	v_mfma_f32_16x16x32_bf16 v[18:21], v[158:161], v[210:213], v[18:21]
	s_setprio 0
	s_barrier
	s_add_i32 s33, s33, s24
	v_lshl_add_u64 v[170:171], s[16:17], 0, v[178:179]
	s_mov_b32 m0, s33
	ds_read_b128 v[162:165], v208 offset:16384
	ds_read_b128 v[166:169], v208 offset:17408
	ds_read_b128 v[184:187], v208 offset:18432
	ds_read_b128 v[188:191], v208 offset:19456
	ds_read_b128 v[192:195], v208 offset:20480
	ds_read_b128 v[196:199], v208 offset:21504
	ds_read_b128 v[200:203], v208 offset:22528
	ds_read_b128 v[210:213], v208 offset:23552
	global_load_lds_dwordx4 v[170:171], off
	s_add_i32 m0, s33, 0x2000
	s_add_u32 s46, s16, 0x80000
	v_lshl_add_u64 v[172:173], s[16:17], 0, v[176:177]
	s_addc_u32 s47, s17, 0
	s_add_i32 s33, s45, s24
	global_load_lds_dwordx4 v[172:173], off
	v_lshl_add_u64 v[204:205], s[46:47], 0, v[178:179]
	s_mov_b32 m0, s33
	v_lshl_add_u64 v[214:215], s[18:19], 0, v[176:177]
	global_load_lds_dwordx4 v[204:205], off
	v_lshl_add_u64 v[204:205], s[46:47], 0, v[176:177]
	s_add_i32 m0, s33, 0x2000
	s_nop 0
	global_load_lds_dwordx4 v[204:205], off
	v_lshl_add_u64 v[204:205], s[18:19], 0, v[178:179]
	s_waitcnt vmcnt(6)
	s_waitcnt lgkmcnt(0)
	s_barrier
	s_setprio 1
	s_waitcnt lgkmcnt(0)
	v_mfma_f32_16x16x32_bf16 v[110:113], v[130:133], v[162:165], v[110:113]
	v_mfma_f32_16x16x32_bf16 v[78:81], v[138:141], v[162:165], v[78:81]
	v_mfma_f32_16x16x32_bf16 v[106:109], v[130:133], v[184:187], v[106:109]
	v_mfma_f32_16x16x32_bf16 v[74:77], v[138:141], v[184:187], v[74:77]
	v_mfma_f32_16x16x32_bf16 v[102:105], v[130:133], v[192:195], v[102:105]
	v_mfma_f32_16x16x32_bf16 v[70:73], v[138:141], v[192:195], v[70:73]
	v_mfma_f32_16x16x32_bf16 v[98:101], v[130:133], v[200:203], v[98:101]
	v_mfma_f32_16x16x32_bf16 v[62:65], v[138:141], v[200:203], v[62:65]
	v_mfma_f32_16x16x32_bf16 v[110:113], v[134:137], v[166:169], v[110:113]
	v_mfma_f32_16x16x32_bf16 v[78:81], v[142:145], v[166:169], v[78:81]
	v_mfma_f32_16x16x32_bf16 v[106:109], v[134:137], v[188:191], v[106:109]
	v_mfma_f32_16x16x32_bf16 v[74:77], v[142:145], v[188:191], v[74:77]
	v_mfma_f32_16x16x32_bf16 v[102:105], v[134:137], v[196:199], v[102:105]
	v_mfma_f32_16x16x32_bf16 v[70:73], v[142:145], v[196:199], v[70:73]
	v_mfma_f32_16x16x32_bf16 v[98:101], v[134:137], v[210:213], v[98:101]
	v_mfma_f32_16x16x32_bf16 v[62:65], v[142:145], v[210:213], v[62:65]
	s_setprio 0
	s_setprio 1
	v_mfma_f32_16x16x32_bf16 v[46:49], v[146:149], v[162:165], v[46:49]
	v_mfma_f32_16x16x32_bf16 v[12:15], v[154:157], v[162:165], v[12:15]
	v_mfma_f32_16x16x32_bf16 v[38:41], v[146:149], v[184:187], v[38:41]
	v_mfma_f32_16x16x32_bf16 v[8:11], v[154:157], v[184:187], v[8:11]
	v_mfma_f32_16x16x32_bf16 v[34:37], v[146:149], v[192:195], v[34:37]
	v_mfma_f32_16x16x32_bf16 v[4:7], v[154:157], v[192:195], v[4:7]
	v_mfma_f32_16x16x32_bf16 v[26:29], v[146:149], v[200:203], v[26:29]
	v_mfma_f32_16x16x32_bf16 v[0:3], v[154:157], v[200:203], v[0:3]
	v_mfma_f32_16x16x32_bf16 v[46:49], v[150:153], v[166:169], v[46:49]
	v_mfma_f32_16x16x32_bf16 v[12:15], v[158:161], v[166:169], v[12:15]
	v_mfma_f32_16x16x32_bf16 v[38:41], v[150:153], v[188:191], v[38:41]
	v_mfma_f32_16x16x32_bf16 v[8:11], v[158:161], v[188:191], v[8:11]
	v_mfma_f32_16x16x32_bf16 v[34:37], v[150:153], v[196:199], v[34:37]
	v_mfma_f32_16x16x32_bf16 v[4:7], v[158:161], v[196:199], v[4:7]
	v_mfma_f32_16x16x32_bf16 v[26:29], v[150:153], v[210:213], v[26:29]
	v_mfma_f32_16x16x32_bf16 v[0:3], v[158:161], v[210:213], v[0:3]
	s_setprio 0
	s_barrier
	s_add_i32 s33, 0, 0x18000
	s_add_i32 s45, 0, 0x1c000
	v_add_u32_e32 v142, s33, v207
	v_add_u32_e32 v158, s45, v207
	ds_read_b128 v[130:133], v142
	ds_read_b128 v[134:137], v142 offset:1024
	ds_read_b128 v[138:141], v142 offset:2048
	ds_read_b128 v[142:145], v142 offset:3072
	ds_read_b128 v[146:149], v158
	ds_read_b128 v[150:153], v158 offset:1024
	ds_read_b128 v[154:157], v158 offset:2048
	ds_read_b128 v[158:161], v158 offset:3072
	s_add_u32 s18, s18, 0x80000
	s_addc_u32 s19, s19, 0
	s_mov_b32 m0, s25
	s_nop 0
	global_load_lds_dwordx4 v[204:205], off
	s_mov_b32 m0, s26
	s_nop 0
	global_load_lds_dwordx4 v[214:215], off
	s_mov_b32 m0, s27
	v_lshl_add_u64 v[222:223], s[18:19], 0, v[178:179]
	ds_read_b128 v[162:165], v208 offset:32768
	ds_read_b128 v[166:169], v208 offset:33792
	ds_read_b128 v[184:187], v208 offset:34816
	ds_read_b128 v[188:191], v208 offset:35840
	ds_read_b128 v[192:195], v208 offset:36864
	ds_read_b128 v[196:199], v208 offset:37888
	ds_read_b128 v[200:203], v208 offset:38912
	ds_read_b128 v[210:213], v208 offset:39936
	global_load_lds_dwordx4 v[222:223], off
	v_lshl_add_u64 v[222:223], s[18:19], 0, v[176:177]
	s_mov_b32 m0, s28
	s_nop 0
	global_load_lds_dwordx4 v[222:223], off
	s_waitcnt vmcnt(8)
	s_waitcnt lgkmcnt(0)
	s_barrier
	s_setprio 1
	s_waitcnt lgkmcnt(0)
	v_mfma_f32_16x16x32_bf16 v[126:129], v[130:133], v[162:165], v[126:129]
	v_mfma_f32_16x16x32_bf16 v[94:97], v[138:141], v[162:165], v[94:97]
	v_mfma_f32_16x16x32_bf16 v[122:125], v[130:133], v[184:187], v[122:125]
	v_mfma_f32_16x16x32_bf16 v[90:93], v[138:141], v[184:187], v[90:93]
	v_mfma_f32_16x16x32_bf16 v[118:121], v[130:133], v[192:195], v[118:121]
	v_mfma_f32_16x16x32_bf16 v[86:89], v[138:141], v[192:195], v[86:89]
	v_mfma_f32_16x16x32_bf16 v[114:117], v[130:133], v[200:203], v[114:117]
	v_mfma_f32_16x16x32_bf16 v[82:85], v[138:141], v[200:203], v[82:85]
	v_mfma_f32_16x16x32_bf16 v[126:129], v[134:137], v[166:169], v[126:129]
	v_mfma_f32_16x16x32_bf16 v[94:97], v[142:145], v[166:169], v[94:97]
	v_mfma_f32_16x16x32_bf16 v[122:125], v[134:137], v[188:191], v[122:125]
	v_mfma_f32_16x16x32_bf16 v[90:93], v[142:145], v[188:191], v[90:93]
	v_mfma_f32_16x16x32_bf16 v[118:121], v[134:137], v[196:199], v[118:121]
	v_mfma_f32_16x16x32_bf16 v[86:89], v[142:145], v[196:199], v[86:89]
	v_mfma_f32_16x16x32_bf16 v[114:117], v[134:137], v[210:213], v[114:117]
	v_mfma_f32_16x16x32_bf16 v[82:85], v[142:145], v[210:213], v[82:85]
	s_setprio 0
	s_setprio 1
	v_mfma_f32_16x16x32_bf16 v[66:69], v[146:149], v[162:165], v[66:69]
	v_mfma_f32_16x16x32_bf16 v[42:45], v[154:157], v[162:165], v[42:45]
	v_mfma_f32_16x16x32_bf16 v[58:61], v[146:149], v[184:187], v[58:61]
	v_mfma_f32_16x16x32_bf16 v[30:33], v[154:157], v[184:187], v[30:33]
	v_mfma_f32_16x16x32_bf16 v[54:57], v[146:149], v[192:195], v[54:57]
	v_mfma_f32_16x16x32_bf16 v[22:25], v[154:157], v[192:195], v[22:25]
	v_mfma_f32_16x16x32_bf16 v[50:53], v[146:149], v[200:203], v[50:53]
	v_mfma_f32_16x16x32_bf16 v[18:21], v[154:157], v[200:203], v[18:21]
	v_mfma_f32_16x16x32_bf16 v[66:69], v[150:153], v[166:169], v[66:69]
	v_mfma_f32_16x16x32_bf16 v[42:45], v[158:161], v[166:169], v[42:45]
	v_mfma_f32_16x16x32_bf16 v[58:61], v[150:153], v[188:191], v[58:61]
	v_mfma_f32_16x16x32_bf16 v[30:33], v[158:161], v[188:191], v[30:33]
	v_mfma_f32_16x16x32_bf16 v[54:57], v[150:153], v[196:199], v[54:57]
	v_mfma_f32_16x16x32_bf16 v[22:25], v[158:161], v[196:199], v[22:25]
	v_mfma_f32_16x16x32_bf16 v[50:53], v[150:153], v[210:213], v[50:53]
	v_mfma_f32_16x16x32_bf16 v[18:21], v[158:161], v[210:213], v[18:21]
	s_setprio 0
	s_barrier
	s_add_i32 s18, s33, s24
	v_lshl_add_u64 v[170:171], v[170:171], 0, s[56:57]
	s_mov_b32 m0, s18
	ds_read_b128 v[162:165], v208 offset:49152
	ds_read_b128 v[166:169], v208 offset:50176
	ds_read_b128 v[184:187], v208 offset:51200
	ds_read_b128 v[188:191], v208 offset:52224
	ds_read_b128 v[192:195], v208 offset:53248
	ds_read_b128 v[196:199], v208 offset:54272
	ds_read_b128 v[200:203], v208 offset:55296
	ds_read_b128 v[210:213], v208 offset:56320
	global_load_lds_dwordx4 v[170:171], off
	s_add_i32 m0, s18, 0x2000
	s_add_u32 s16, s16, 0x80080
	v_lshl_add_u64 v[170:171], v[172:173], 0, s[56:57]
	s_addc_u32 s17, s17, 0
	s_add_i32 s18, s45, s24
	global_load_lds_dwordx4 v[170:171], off
	v_lshl_add_u64 v[170:171], s[16:17], 0, v[178:179]
	s_mov_b32 m0, s18
	s_nop 0
	global_load_lds_dwordx4 v[170:171], off
	v_lshl_add_u64 v[170:171], s[16:17], 0, v[176:177]
	s_add_i32 m0, s18, 0x2000
	s_nop 0
	global_load_lds_dwordx4 v[170:171], off
	s_cmp_eq_u32 s44, 28
	s_cbranch_scc0 .Lbal_out_notlast
	v_lshl_add_u64 v[170:171], v[204:205], 0, s[56:57]
	s_mov_b32 m0, s35
	s_nop 0
	global_load_lds_dwordx4 v[170:171], off
	v_lshl_add_u64 v[170:171], v[214:215], 0, s[56:57]
	s_mov_b32 m0, s36
	s_nop 0
	global_load_lds_dwordx4 v[170:171], off
	s_waitcnt vmcnt(8)
	s_branch .Lbal_out_join

.Lbal_out_join:
	s_waitcnt lgkmcnt(0)
	s_barrier
	s_setprio 1
	s_waitcnt lgkmcnt(0)
	v_mfma_f32_16x16x32_bf16 v[110:113], v[130:133], v[162:165], v[110:113]
	v_mfma_f32_16x16x32_bf16 v[78:81], v[138:141], v[162:165], v[78:81]
	v_mfma_f32_16x16x32_bf16 v[106:109], v[130:133], v[184:187], v[106:109]
	v_mfma_f32_16x16x32_bf16 v[74:77], v[138:141], v[184:187], v[74:77]
	v_mfma_f32_16x16x32_bf16 v[102:105], v[130:133], v[192:195], v[102:105]
	v_mfma_f32_16x16x32_bf16 v[70:73], v[138:141], v[192:195], v[70:73]
	v_mfma_f32_16x16x32_bf16 v[98:101], v[130:133], v[200:203], v[98:101]
	v_mfma_f32_16x16x32_bf16 v[62:65], v[138:141], v[200:203], v[62:65]
	v_mfma_f32_16x16x32_bf16 v[110:113], v[134:137], v[166:169], v[110:113]
	v_mfma_f32_16x16x32_bf16 v[78:81], v[142:145], v[166:169], v[78:81]
	v_mfma_f32_16x16x32_bf16 v[106:109], v[134:137], v[188:191], v[106:109]
	v_mfma_f32_16x16x32_bf16 v[74:77], v[142:145], v[188:191], v[74:77]
	v_mfma_f32_16x16x32_bf16 v[102:105], v[134:137], v[196:199], v[102:105]
	v_mfma_f32_16x16x32_bf16 v[70:73], v[142:145], v[196:199], v[70:73]
	v_mfma_f32_16x16x32_bf16 v[98:101], v[134:137], v[210:213], v[98:101]
	v_mfma_f32_16x16x32_bf16 v[62:65], v[142:145], v[210:213], v[62:65]
	s_setprio 0
	s_setprio 1
	v_mfma_f32_16x16x32_bf16 v[46:49], v[146:149], v[162:165], v[46:49]
	v_mfma_f32_16x16x32_bf16 v[12:15], v[154:157], v[162:165], v[12:15]
	v_mfma_f32_16x16x32_bf16 v[38:41], v[146:149], v[184:187], v[38:41]
	v_mfma_f32_16x16x32_bf16 v[8:11], v[154:157], v[184:187], v[8:11]
	v_mfma_f32_16x16x32_bf16 v[34:37], v[146:149], v[192:195], v[34:37]
	v_mfma_f32_16x16x32_bf16 v[4:7], v[154:157], v[192:195], v[4:7]
	v_mfma_f32_16x16x32_bf16 v[26:29], v[146:149], v[200:203], v[26:29]
	v_mfma_f32_16x16x32_bf16 v[0:3], v[154:157], v[200:203], v[0:3]
	v_mfma_f32_16x16x32_bf16 v[46:49], v[150:153], v[166:169], v[46:49]
	v_mfma_f32_16x16x32_bf16 v[12:15], v[158:161], v[166:169], v[12:15]
	v_mfma_f32_16x16x32_bf16 v[38:41], v[150:153], v[188:191], v[38:41]
	v_mfma_f32_16x16x32_bf16 v[8:11], v[158:161], v[188:191], v[8:11]
	v_mfma_f32_16x16x32_bf16 v[34:37], v[150:153], v[196:199], v[34:37]
	v_mfma_f32_16x16x32_bf16 v[4:7], v[158:161], v[196:199], v[4:7]
	v_mfma_f32_16x16x32_bf16 v[26:29], v[150:153], v[210:213], v[26:29]
	v_mfma_f32_16x16x32_bf16 v[0:3], v[158:161], v[210:213], v[0:3]
	s_setprio 0
	s_barrier
	s_add_i32 s44, s44, 2
	s_add_u32 s14, s14, 0x100
	s_addc_u32 s15, s15, 0
	s_add_u32 s42, s42, 0x100
	s_addc_u32 s43, s43, 0
	s_cmp_gt_u32 s44, 29
	s_cbranch_scc0 .LBB0_108
	s_and_b64 vcc, exec, s[2:3]
	s_movk_i32 s44, 0x1000
	s_cbranch_vccz .LBB0_111
	s_barrier

.LBB0_552:
	s_add_u32 s8, s6, 0xfffe0080
	s_addc_u32 s9, s7, -1
	s_add_i32 s47, 0, 0x10000
	s_cmp_eq_u32 s46, 4
	s_cselect_b32 s25, s19, s9
	s_cselect_b32 s24, s42, s8
	s_cselect_b32 s9, s17, s45
	s_cselect_b32 s8, s43, s44
	s_add_i32 s50, 0, 0x14000
	v_add_u32_e32 v86, s47, v184
	v_add_u32_e32 v168, s50, v184
	ds_read_b128 v[58:61], v86
	ds_read_b128 v[70:73], v86 offset:1024
	ds_read_b128 v[74:77], v86 offset:2048
	ds_read_b128 v[86:89], v86 offset:3072
	ds_read_b128 v[122:125], v168
	ds_read_b128 v[126:129], v168 offset:1024
	ds_read_b128 v[154:157], v168 offset:2048
	ds_read_b128 v[176:179], v168 offset:3072
	s_cmp_eq_u32 s46, -2
	s_cbranch_scc1 .Lbal_glu_first
	v_lshl_add_u64 v[168:169], v[172:173], 0, s[56:57]
	s_mov_b32 m0, s38
	s_nop 0
	global_load_lds_dwordx4 v[168:169], off
	v_lshl_add_u64 v[168:169], v[180:181], 0, s[56:57]
	s_mov_b32 m0, s39
	s_nop 0
	global_load_lds_dwordx4 v[168:169], off
.Lbal_glu_first:
	v_lshl_add_u64 v[168:169], s[6:7], 0, v[164:165]
	s_add_i32 m0, s31, 0xc000
	ds_read_b128 v[186:189], v185
	ds_read_b128 v[190:193], v185 offset:1024
	ds_read_b128 v[194:197], v185 offset:2048
	ds_read_b128 v[198:201], v185 offset:3072
	ds_read_b128 v[202:205], v185 offset:4096
	ds_read_b128 v[206:209], v185 offset:5120
	ds_read_b128 v[210:213], v185 offset:6144
	ds_read_b128 v[230:233], v185 offset:7168
	global_load_lds_dwordx4 v[168:169], off
	v_lshl_add_u64 v[168:169], s[6:7], 0, v[166:167]
	s_add_i32 m0, s31, 0xe000
	s_nop 0
	global_load_lds_dwordx4 v[168:169], off
	s_waitcnt vmcnt(8)
	s_waitcnt lgkmcnt(0)
	s_barrier
	s_setprio 1
	s_waitcnt lgkmcnt(0)
	v_mfma_f32_16x16x32_bf16 v[150:153], v[58:61], v[186:189], v[150:153]
	v_mfma_f32_16x16x32_bf16 v[146:149], v[74:77], v[186:189], v[146:149]
	v_mfma_f32_16x16x32_bf16 v[142:145], v[58:61], v[194:197], v[142:145]
	v_mfma_f32_16x16x32_bf16 v[138:141], v[74:77], v[194:197], v[138:141]
	v_mfma_f32_16x16x32_bf16 v[134:137], v[58:61], v[202:205], v[134:137]
	v_mfma_f32_16x16x32_bf16 v[130:133], v[74:77], v[202:205], v[130:133]
	v_mfma_f32_16x16x32_bf16 v[118:121], v[58:61], v[210:213], v[118:121]
	v_mfma_f32_16x16x32_bf16 v[114:117], v[74:77], v[210:213], v[114:117]
	v_mfma_f32_16x16x32_bf16 v[150:153], v[70:73], v[190:193], v[150:153]
	v_mfma_f32_16x16x32_bf16 v[146:149], v[86:89], v[190:193], v[146:149]
	v_mfma_f32_16x16x32_bf16 v[142:145], v[70:73], v[198:201], v[142:145]
	v_mfma_f32_16x16x32_bf16 v[138:141], v[86:89], v[198:201], v[138:141]
	v_mfma_f32_16x16x32_bf16 v[134:137], v[70:73], v[206:209], v[134:137]
	v_mfma_f32_16x16x32_bf16 v[130:133], v[86:89], v[206:209], v[130:133]
	v_mfma_f32_16x16x32_bf16 v[118:121], v[70:73], v[230:233], v[118:121]
	v_mfma_f32_16x16x32_bf16 v[114:117], v[86:89], v[230:233], v[114:117]
	s_setprio 0
	s_setprio 1
	v_mfma_f32_16x16x32_bf16 v[66:69], v[122:125], v[186:189], v[66:69]
	v_mfma_f32_16x16x32_bf16 v[62:65], v[154:157], v[186:189], v[62:65]
	v_mfma_f32_16x16x32_bf16 v[54:57], v[122:125], v[194:197], v[54:57]
	v_mfma_f32_16x16x32_bf16 v[50:53], v[154:157], v[194:197], v[50:53]
	v_mfma_f32_16x16x32_bf16 v[46:49], v[122:125], v[202:205], v[46:49]
	v_mfma_f32_16x16x32_bf16 v[42:45], v[154:157], v[202:205], v[42:45]
	v_mfma_f32_16x16x32_bf16 v[38:41], v[122:125], v[210:213], v[38:41]
	v_mfma_f32_16x16x32_bf16 v[34:37], v[154:157], v[210:213], v[34:37]
	v_mfma_f32_16x16x32_bf16 v[66:69], v[126:129], v[190:193], v[66:69]
	v_mfma_f32_16x16x32_bf16 v[62:65], v[176:179], v[190:193], v[62:65]
	v_mfma_f32_16x16x32_bf16 v[54:57], v[126:129], v[198:201], v[54:57]
	v_mfma_f32_16x16x32_bf16 v[50:53], v[176:179], v[198:201], v[50:53]
	v_mfma_f32_16x16x32_bf16 v[46:49], v[126:129], v[206:209], v[46:49]
	v_mfma_f32_16x16x32_bf16 v[42:45], v[176:179], v[206:209], v[42:45]
	v_mfma_f32_16x16x32_bf16 v[38:41], v[126:129], v[230:233], v[38:41]
	v_mfma_f32_16x16x32_bf16 v[34:37], v[176:179], v[230:233], v[34:37]
	s_setprio 0
	s_barrier
	s_add_i32 s47, s47, s30
	v_lshl_add_u64 v[168:169], s[8:9], 0, v[16:17]
	s_mov_b32 m0, s47
	ds_read_b128 v[186:189], v185 offset:16384
	ds_read_b128 v[190:193], v185 offset:17408
	ds_read_b128 v[194:197], v185 offset:18432
	ds_read_b128 v[198:201], v185 offset:19456
	ds_read_b128 v[202:205], v185 offset:20480
	ds_read_b128 v[206:209], v185 offset:21504
	ds_read_b128 v[210:213], v185 offset:22528
	ds_read_b128 v[230:233], v185 offset:23552
	global_load_lds_dwordx4 v[168:169], off
	s_add_i32 m0, s47, 0x2000
	s_add_u32 s48, s8, 0x20000
	v_lshl_add_u64 v[170:171], s[8:9], 0, v[158:159]
	s_addc_u32 s49, s9, 0
	s_add_i32 s47, s50, s30
	global_load_lds_dwordx4 v[170:171], off
	v_lshl_add_u64 v[172:173], s[48:49], 0, v[16:17]
	s_mov_b32 m0, s47
	v_lshl_add_u64 v[180:181], s[24:25], 0, v[160:161]
	global_load_lds_dwordx4 v[172:173], off
	v_lshl_add_u64 v[172:173], s[48:49], 0, v[158:159]
	s_add_i32 m0, s47, 0x2000
	s_nop 0
	global_load_lds_dwordx4 v[172:173], off
	v_lshl_add_u64 v[172:173], s[24:25], 0, v[162:163]
	s_waitcnt vmcnt(6)
	s_waitcnt lgkmcnt(0)
	s_barrier
	s_setprio 1
	s_waitcnt lgkmcnt(0)
	v_mfma_f32_16x16x32_bf16 v[110:113], v[58:61], v[186:189], v[110:113]
	v_mfma_f32_16x16x32_bf16 v[106:109], v[74:77], v[186:189], v[106:109]
	v_mfma_f32_16x16x32_bf16 v[102:105], v[58:61], v[194:197], v[102:105]
	v_mfma_f32_16x16x32_bf16 v[98:101], v[74:77], v[194:197], v[98:101]
	v_mfma_f32_16x16x32_bf16 v[94:97], v[58:61], v[202:205], v[94:97]
	v_mfma_f32_16x16x32_bf16 v[90:93], v[74:77], v[202:205], v[90:93]
	v_mfma_f32_16x16x32_bf16 v[58:61], v[58:61], v[210:213], v[82:85]
	v_mfma_f32_16x16x32_bf16 v[110:113], v[70:73], v[190:193], v[110:113]
	v_mfma_f32_16x16x32_bf16 v[106:109], v[86:89], v[190:193], v[106:109]
	v_mfma_f32_16x16x32_bf16 v[102:105], v[70:73], v[198:201], v[102:105]
	v_mfma_f32_16x16x32_bf16 v[98:101], v[86:89], v[198:201], v[98:101]
	v_mfma_f32_16x16x32_bf16 v[94:97], v[70:73], v[206:209], v[94:97]
	v_mfma_f32_16x16x32_bf16 v[90:93], v[86:89], v[206:209], v[90:93]
	v_mfma_f32_16x16x32_bf16 v[58:61], v[70:73], v[230:233], v[58:61]
	v_mfma_f32_16x16x32_bf16 v[70:73], v[74:77], v[210:213], v[78:81]
	v_mfma_f32_16x16x32_bf16 v[70:73], v[86:89], v[230:233], v[70:73]
	s_setprio 0
	s_setprio 1
	v_mfma_f32_16x16x32_bf16 v[30:33], v[122:125], v[186:189], v[30:33]
	v_mfma_f32_16x16x32_bf16 v[26:29], v[154:157], v[186:189], v[26:29]
	v_mfma_f32_16x16x32_bf16 v[22:25], v[122:125], v[194:197], v[22:25]
	v_mfma_f32_16x16x32_bf16 v[18:21], v[154:157], v[194:197], v[18:21]
	v_mfma_f32_16x16x32_bf16 v[12:15], v[122:125], v[202:205], v[12:15]
	v_mfma_f32_16x16x32_bf16 v[8:11], v[154:157], v[202:205], v[8:11]
	v_mfma_f32_16x16x32_bf16 v[4:7], v[122:125], v[210:213], v[4:7]
	v_mfma_f32_16x16x32_bf16 v[0:3], v[154:157], v[210:213], v[0:3]
	v_mfma_f32_16x16x32_bf16 v[30:33], v[126:129], v[190:193], v[30:33]
	v_mfma_f32_16x16x32_bf16 v[26:29], v[176:179], v[190:193], v[26:29]
	v_mfma_f32_16x16x32_bf16 v[22:25], v[126:129], v[198:201], v[22:25]
	v_mfma_f32_16x16x32_bf16 v[18:21], v[176:179], v[198:201], v[18:21]
	v_mfma_f32_16x16x32_bf16 v[12:15], v[126:129], v[206:209], v[12:15]
	v_mfma_f32_16x16x32_bf16 v[8:11], v[176:179], v[206:209], v[8:11]
	v_mfma_f32_16x16x32_bf16 v[4:7], v[126:129], v[230:233], v[4:7]
	v_mfma_f32_16x16x32_bf16 v[0:3], v[176:179], v[230:233], v[0:3]
	s_setprio 0
	s_barrier
	s_add_i32 s47, 0, 0x18000
	v_add_u32_e32 v82, s47, v184
	s_add_i32 s48, 0, 0x1c000
	ds_read_b128 v[74:77], v82
	ds_read_b128 v[78:81], v82 offset:1024
	ds_read_b128 v[86:89], v82 offset:2048
	ds_read_b128 v[122:125], v82 offset:3072
	v_add_u32_e32 v82, s48, v184
	ds_read_b128 v[126:129], v82
	ds_read_b128 v[154:157], v82 offset:1024
	ds_read_b128 v[176:179], v82 offset:2048
	ds_read_b128 v[186:189], v82 offset:3072
	s_add_u32 s24, s24, 0x20000
	s_addc_u32 s25, s25, 0
	s_mov_b32 m0, s31
	s_nop 0
	global_load_lds_dwordx4 v[172:173], off
	s_mov_b32 m0, s34
	s_nop 0
	global_load_lds_dwordx4 v[180:181], off
	s_mov_b32 m0, s35
	v_lshl_add_u64 v[214:215], s[24:25], 0, v[162:163]
	ds_read_b128 v[82:85], v185 offset:32768
	ds_read_b128 v[190:193], v185 offset:33792
	ds_read_b128 v[194:197], v185 offset:34816
	ds_read_b128 v[198:201], v185 offset:35840
	ds_read_b128 v[202:205], v185 offset:36864
	ds_read_b128 v[206:209], v185 offset:37888
	ds_read_b128 v[210:213], v185 offset:38912
	ds_read_b128 v[230:233], v185 offset:39936
	global_load_lds_dwordx4 v[214:215], off
	v_lshl_add_u64 v[214:215], s[24:25], 0, v[160:161]
	s_mov_b32 m0, s36
	s_nop 0
	global_load_lds_dwordx4 v[214:215], off
	s_waitcnt vmcnt(8)
	s_waitcnt lgkmcnt(0)
	s_barrier
	s_setprio 1
	s_waitcnt lgkmcnt(0)
	v_mfma_f32_16x16x32_bf16 v[150:153], v[74:77], v[82:85], v[150:153]
	v_mfma_f32_16x16x32_bf16 v[146:149], v[86:89], v[82:85], v[146:149]
	v_mfma_f32_16x16x32_bf16 v[142:145], v[74:77], v[194:197], v[142:145]
	v_mfma_f32_16x16x32_bf16 v[138:141], v[86:89], v[194:197], v[138:141]
	v_mfma_f32_16x16x32_bf16 v[134:137], v[74:77], v[202:205], v[134:137]
	v_mfma_f32_16x16x32_bf16 v[130:133], v[86:89], v[202:205], v[130:133]
	v_mfma_f32_16x16x32_bf16 v[118:121], v[74:77], v[210:213], v[118:121]
	v_mfma_f32_16x16x32_bf16 v[114:117], v[86:89], v[210:213], v[114:117]
	v_mfma_f32_16x16x32_bf16 v[150:153], v[78:81], v[190:193], v[150:153]
	v_mfma_f32_16x16x32_bf16 v[146:149], v[122:125], v[190:193], v[146:149]
	v_mfma_f32_16x16x32_bf16 v[142:145], v[78:81], v[198:201], v[142:145]
	v_mfma_f32_16x16x32_bf16 v[138:141], v[122:125], v[198:201], v[138:141]
	v_mfma_f32_16x16x32_bf16 v[134:137], v[78:81], v[206:209], v[134:137]
	v_mfma_f32_16x16x32_bf16 v[130:133], v[122:125], v[206:209], v[130:133]
	v_mfma_f32_16x16x32_bf16 v[118:121], v[78:81], v[230:233], v[118:121]
	v_mfma_f32_16x16x32_bf16 v[114:117], v[122:125], v[230:233], v[114:117]
	s_setprio 0
	s_setprio 1
	v_mfma_f32_16x16x32_bf16 v[66:69], v[126:129], v[82:85], v[66:69]
	v_mfma_f32_16x16x32_bf16 v[62:65], v[176:179], v[82:85], v[62:65]
	v_mfma_f32_16x16x32_bf16 v[54:57], v[126:129], v[194:197], v[54:57]
	v_mfma_f32_16x16x32_bf16 v[50:53], v[176:179], v[194:197], v[50:53]
	v_mfma_f32_16x16x32_bf16 v[46:49], v[126:129], v[202:205], v[46:49]
	v_mfma_f32_16x16x32_bf16 v[42:45], v[176:179], v[202:205], v[42:45]
	v_mfma_f32_16x16x32_bf16 v[38:41], v[126:129], v[210:213], v[38:41]
	v_mfma_f32_16x16x32_bf16 v[34:37], v[176:179], v[210:213], v[34:37]
	v_mfma_f32_16x16x32_bf16 v[66:69], v[154:157], v[190:193], v[66:69]
	v_mfma_f32_16x16x32_bf16 v[62:65], v[186:189], v[190:193], v[62:65]
	v_mfma_f32_16x16x32_bf16 v[54:57], v[154:157], v[198:201], v[54:57]
	v_mfma_f32_16x16x32_bf16 v[50:53], v[186:189], v[198:201], v[50:53]
	v_mfma_f32_16x16x32_bf16 v[46:49], v[154:157], v[206:209], v[46:49]
	v_mfma_f32_16x16x32_bf16 v[42:45], v[186:189], v[206:209], v[42:45]
	v_mfma_f32_16x16x32_bf16 v[38:41], v[154:157], v[230:233], v[38:41]
	v_mfma_f32_16x16x32_bf16 v[34:37], v[186:189], v[230:233], v[34:37]
	s_setprio 0
	s_barrier
	s_add_i32 s24, s47, s30
	v_lshl_add_u64 v[82:83], v[168:169], 0, s[56:57]
	s_mov_b32 m0, s24
	ds_read_b128 v[190:193], v185 offset:49152
	ds_read_b128 v[194:197], v185 offset:50176
	ds_read_b128 v[198:201], v185 offset:51200
	ds_read_b128 v[202:205], v185 offset:52224
	ds_read_b128 v[206:209], v185 offset:53248
	ds_read_b128 v[210:213], v185 offset:54272
	ds_read_b128 v[230:233], v185 offset:55296
	ds_read_b128 v[234:237], v185 offset:56320
	global_load_lds_dwordx4 v[82:83], off
	s_add_i32 m0, s24, 0x2000
	s_add_u32 s8, s8, 0x20080
	v_lshl_add_u64 v[82:83], v[170:171], 0, s[56:57]
	s_addc_u32 s9, s9, 0
	s_add_i32 s24, s48, s30
	global_load_lds_dwordx4 v[82:83], off
	v_lshl_add_u64 v[82:83], s[8:9], 0, v[16:17]
	s_mov_b32 m0, s24
	s_nop 0
	global_load_lds_dwordx4 v[82:83], off
	v_lshl_add_u64 v[82:83], s[8:9], 0, v[158:159]
	s_add_i32 m0, s24, 0x2000
	s_nop 0
	global_load_lds_dwordx4 v[82:83], off
	s_cmp_eq_u32 s46, 4
	s_cbranch_scc0 .Lbal_glu_notlast
	v_lshl_add_u64 v[82:83], v[172:173], 0, s[56:57]
	s_mov_b32 m0, s38
	s_nop 0
	global_load_lds_dwordx4 v[82:83], off
	v_lshl_add_u64 v[82:83], v[180:181], 0, s[56:57]
	s_mov_b32 m0, s39
	s_nop 0
	global_load_lds_dwordx4 v[82:83], off
	s_waitcnt vmcnt(8)
	s_branch .Lbal_glu_join

.Lbal_glu_join:
	s_waitcnt lgkmcnt(0)
	s_barrier
	s_setprio 1
	s_waitcnt lgkmcnt(0)
	v_mfma_f32_16x16x32_bf16 v[82:85], v[74:77], v[190:193], v[110:113]
	v_mfma_f32_16x16x32_bf16 v[110:113], v[78:81], v[194:197], v[82:85]
	v_mfma_f32_16x16x32_bf16 v[82:85], v[86:89], v[190:193], v[106:109]
	v_mfma_f32_16x16x32_bf16 v[106:109], v[122:125], v[194:197], v[82:85]
	v_mfma_f32_16x16x32_bf16 v[82:85], v[74:77], v[198:201], v[102:105]
	v_mfma_f32_16x16x32_bf16 v[102:105], v[78:81], v[202:205], v[82:85]
	v_mfma_f32_16x16x32_bf16 v[82:85], v[86:89], v[198:201], v[98:101]
	v_mfma_f32_16x16x32_bf16 v[98:101], v[122:125], v[202:205], v[82:85]
	v_mfma_f32_16x16x32_bf16 v[82:85], v[74:77], v[206:209], v[94:97]
	v_mfma_f32_16x16x32_bf16 v[94:97], v[78:81], v[210:213], v[82:85]
	v_mfma_f32_16x16x32_bf16 v[82:85], v[86:89], v[206:209], v[90:93]
	v_mfma_f32_16x16x32_bf16 v[58:61], v[74:77], v[230:233], v[58:61]
	v_mfma_f32_16x16x32_bf16 v[90:93], v[122:125], v[210:213], v[82:85]
	v_mfma_f32_16x16x32_bf16 v[82:85], v[78:81], v[234:237], v[58:61]
	v_mfma_f32_16x16x32_bf16 v[58:61], v[86:89], v[230:233], v[70:73]
	v_mfma_f32_16x16x32_bf16 v[78:81], v[122:125], v[234:237], v[58:61]
	s_setprio 0
	s_setprio 1
	v_mfma_f32_16x16x32_bf16 v[30:33], v[126:129], v[190:193], v[30:33]
	v_mfma_f32_16x16x32_bf16 v[26:29], v[176:179], v[190:193], v[26:29]
	v_mfma_f32_16x16x32_bf16 v[22:25], v[126:129], v[198:201], v[22:25]
	v_mfma_f32_16x16x32_bf16 v[18:21], v[176:179], v[198:201], v[18:21]
	v_mfma_f32_16x16x32_bf16 v[12:15], v[126:129], v[206:209], v[12:15]
	v_mfma_f32_16x16x32_bf16 v[8:11], v[176:179], v[206:209], v[8:11]
	v_mfma_f32_16x16x32_bf16 v[4:7], v[126:129], v[230:233], v[4:7]
	v_mfma_f32_16x16x32_bf16 v[0:3], v[176:179], v[230:233], v[0:3]
	v_mfma_f32_16x16x32_bf16 v[30:33], v[154:157], v[194:197], v[30:33]
	v_mfma_f32_16x16x32_bf16 v[26:29], v[186:189], v[194:197], v[26:29]
	v_mfma_f32_16x16x32_bf16 v[22:25], v[154:157], v[202:205], v[22:25]
	v_mfma_f32_16x16x32_bf16 v[18:21], v[186:189], v[202:205], v[18:21]
	v_mfma_f32_16x16x32_bf16 v[12:15], v[154:157], v[210:213], v[12:15]
	v_mfma_f32_16x16x32_bf16 v[8:11], v[186:189], v[210:213], v[8:11]
	v_mfma_f32_16x16x32_bf16 v[4:7], v[154:157], v[234:237], v[4:7]
	v_mfma_f32_16x16x32_bf16 v[0:3], v[186:189], v[234:237], v[0:3]
	s_setprio 0
	s_barrier
	s_add_i32 s46, s46, 2
	s_add_u32 s6, s6, 0x100
	s_addc_u32 s7, s7, 0
	s_add_u32 s44, s44, 0x100
	s_addc_u32 s45, s45, 0
	s_cmp_gt_u32 s46, 5
	s_cbranch_scc0 .LBB0_552
	s_and_b64 vcc, exec, s[14:15]
	s_cbranch_vccz .LBB0_555
	s_barrier

.LBB0_1018:
	s_add_u32 s26, s24, 0xfff80080
	s_addc_u32 s27, s25, -1
	s_add_i32 s63, 0, 0x10000
	s_cmp_eq_u32 s62, 28
	s_cselect_b32 s29, s19, s27
	s_cselect_b32 s28, s31, s26
	v_add_u32_e32 v16, s63, v166
	s_cselect_b32 s27, s17, s61
	s_cselect_b32 s26, s55, s60
	s_add_i32 s66, 0, 0x14000
	ds_read_b128 v[144:147], v16
	ds_read_b128 v[148:151], v16 offset:1024
	ds_read_b128 v[152:155], v16 offset:2048
	ds_read_b128 v[156:159], v16 offset:3072
	v_add_u32_e32 v16, s66, v166
	ds_read_b128 v[160:163], v16
	ds_read_b128 v[176:179], v16 offset:1024
	ds_read_b128 v[180:183], v16 offset:2048
	ds_read_b128 v[184:187], v16 offset:3072
	s_cmp_eq_u32 s62, -2
	s_cbranch_scc1 .Lbal_g1_first
	v_lshl_add_u64 v[168:169], v[172:173], 0, s[56:57]
	s_mov_b32 m0, s46
	s_nop 0
	global_load_lds_dwordx4 v[168:169], off
	v_lshl_add_u64 v[168:169], v[222:223], 0, s[56:57]
	s_mov_b32 m0, s47
	s_nop 0
	global_load_lds_dwordx4 v[168:169], off
.Lbal_g1_first:
	v_lshl_add_u64 v[168:169], s[24:25], 0, v[140:141]
	s_add_i32 m0, s39, 0xc000
	ds_read_b128 v[188:191], v167
	ds_read_b128 v[192:195], v167 offset:1024
	ds_read_b128 v[196:199], v167 offset:2048
	ds_read_b128 v[200:203], v167 offset:3072
	ds_read_b128 v[204:207], v167 offset:4096
	ds_read_b128 v[208:211], v167 offset:5120
	ds_read_b128 v[212:215], v167 offset:6144
	ds_read_b128 v[230:233], v167 offset:7168
	global_load_lds_dwordx4 v[168:169], off
	v_lshl_add_u64 v[168:169], s[24:25], 0, v[142:143]
	s_add_i32 m0, s39, 0xe000
	s_nop 0
	global_load_lds_dwordx4 v[168:169], off
	s_waitcnt vmcnt(8)
	s_waitcnt lgkmcnt(0)
	s_barrier
	s_setprio 1
	s_waitcnt lgkmcnt(0)
	v_mfma_f32_16x16x32_bf16 v[66:69], v[144:147], v[188:191], v[66:69]
	v_mfma_f32_16x16x32_bf16 v[62:65], v[152:155], v[188:191], v[62:65]
	v_mfma_f32_16x16x32_bf16 v[58:61], v[144:147], v[196:199], v[58:61]
	v_mfma_f32_16x16x32_bf16 v[54:57], v[152:155], v[196:199], v[54:57]
	v_mfma_f32_16x16x32_bf16 v[46:49], v[144:147], v[204:207], v[46:49]
	v_mfma_f32_16x16x32_bf16 v[42:45], v[152:155], v[204:207], v[42:45]
	v_mfma_f32_16x16x32_bf16 v[38:41], v[144:147], v[212:215], v[38:41]
	v_mfma_f32_16x16x32_bf16 v[34:37], v[152:155], v[212:215], v[34:37]
	v_mfma_f32_16x16x32_bf16 v[66:69], v[148:151], v[192:195], v[66:69]
	v_mfma_f32_16x16x32_bf16 v[62:65], v[156:159], v[192:195], v[62:65]
	v_mfma_f32_16x16x32_bf16 v[58:61], v[148:151], v[200:203], v[58:61]
	v_mfma_f32_16x16x32_bf16 v[54:57], v[156:159], v[200:203], v[54:57]
	v_mfma_f32_16x16x32_bf16 v[46:49], v[148:151], v[208:211], v[46:49]
	v_mfma_f32_16x16x32_bf16 v[42:45], v[156:159], v[208:211], v[42:45]
	v_mfma_f32_16x16x32_bf16 v[38:41], v[148:151], v[230:233], v[38:41]
	v_mfma_f32_16x16x32_bf16 v[34:37], v[156:159], v[230:233], v[34:37]
	s_setprio 0
	s_setprio 1
	v_mfma_f32_16x16x32_bf16 v[126:129], v[160:163], v[188:191], v[126:129]
	v_mfma_f32_16x16x32_bf16 v[122:125], v[180:183], v[188:191], v[122:125]
	v_mfma_f32_16x16x32_bf16 v[118:121], v[160:163], v[196:199], v[118:121]
	v_mfma_f32_16x16x32_bf16 v[114:117], v[180:183], v[196:199], v[114:117]
	v_mfma_f32_16x16x32_bf16 v[110:113], v[160:163], v[204:207], v[110:113]
	v_mfma_f32_16x16x32_bf16 v[106:109], v[180:183], v[204:207], v[106:109]
	v_mfma_f32_16x16x32_bf16 v[102:105], v[160:163], v[212:215], v[102:105]
	v_mfma_f32_16x16x32_bf16 v[98:101], v[180:183], v[212:215], v[98:101]
	v_mfma_f32_16x16x32_bf16 v[126:129], v[176:179], v[192:195], v[126:129]
	v_mfma_f32_16x16x32_bf16 v[122:125], v[184:187], v[192:195], v[122:125]
	v_mfma_f32_16x16x32_bf16 v[118:121], v[176:179], v[200:203], v[118:121]
	v_mfma_f32_16x16x32_bf16 v[114:117], v[184:187], v[200:203], v[114:117]
	v_mfma_f32_16x16x32_bf16 v[110:113], v[176:179], v[208:211], v[110:113]
	v_mfma_f32_16x16x32_bf16 v[106:109], v[184:187], v[208:211], v[106:109]
	v_mfma_f32_16x16x32_bf16 v[102:105], v[176:179], v[230:233], v[102:105]
	v_mfma_f32_16x16x32_bf16 v[98:101], v[184:187], v[230:233], v[98:101]
	s_setprio 0
	s_barrier
	s_add_i32 s63, s63, s38
	v_lshl_add_u64 v[168:169], s[26:27], 0, v[132:133]
	s_mov_b32 m0, s63
	ds_read_b128 v[188:191], v167 offset:16384
	ds_read_b128 v[192:195], v167 offset:17408
	ds_read_b128 v[196:199], v167 offset:18432
	ds_read_b128 v[200:203], v167 offset:19456
	ds_read_b128 v[204:207], v167 offset:20480
	ds_read_b128 v[208:211], v167 offset:21504
	ds_read_b128 v[212:215], v167 offset:22528
	ds_read_b128 v[230:233], v167 offset:23552
	global_load_lds_dwordx4 v[168:169], off
	s_add_i32 m0, s63, 0x2000
	s_add_u32 s64, s26, 0x80000
	v_lshl_add_u64 v[170:171], s[26:27], 0, v[136:137]
	s_addc_u32 s65, s27, 0
	s_add_i32 s63, s66, s38
	global_load_lds_dwordx4 v[170:171], off
	v_lshl_add_u64 v[172:173], s[64:65], 0, v[132:133]
	s_mov_b32 m0, s63
	v_lshl_add_u64 v[222:223], s[28:29], 0, v[134:135]
	global_load_lds_dwordx4 v[172:173], off
	v_lshl_add_u64 v[172:173], s[64:65], 0, v[136:137]
	s_add_i32 m0, s63, 0x2000
	s_nop 0
	global_load_lds_dwordx4 v[172:173], off
	v_lshl_add_u64 v[172:173], s[28:29], 0, v[130:131]
	s_waitcnt vmcnt(6)
	s_waitcnt lgkmcnt(0)
	s_barrier
	s_setprio 1
	s_waitcnt lgkmcnt(0)
	v_mfma_f32_16x16x32_bf16 v[30:33], v[144:147], v[188:191], v[30:33]
	v_mfma_f32_16x16x32_bf16 v[26:29], v[152:155], v[188:191], v[26:29]
	v_mfma_f32_16x16x32_bf16 v[22:25], v[144:147], v[196:199], v[22:25]
	v_mfma_f32_16x16x32_bf16 v[18:21], v[152:155], v[196:199], v[18:21]
	v_mfma_f32_16x16x32_bf16 v[12:15], v[144:147], v[204:207], v[12:15]
	v_mfma_f32_16x16x32_bf16 v[8:11], v[152:155], v[204:207], v[8:11]
	v_mfma_f32_16x16x32_bf16 v[4:7], v[144:147], v[212:215], v[4:7]
	v_mfma_f32_16x16x32_bf16 v[0:3], v[152:155], v[212:215], v[0:3]
	v_mfma_f32_16x16x32_bf16 v[30:33], v[148:151], v[192:195], v[30:33]
	v_mfma_f32_16x16x32_bf16 v[26:29], v[156:159], v[192:195], v[26:29]
	v_mfma_f32_16x16x32_bf16 v[22:25], v[148:151], v[200:203], v[22:25]
	v_mfma_f32_16x16x32_bf16 v[18:21], v[156:159], v[200:203], v[18:21]
	v_mfma_f32_16x16x32_bf16 v[12:15], v[148:151], v[208:211], v[12:15]
	v_mfma_f32_16x16x32_bf16 v[8:11], v[156:159], v[208:211], v[8:11]
	v_mfma_f32_16x16x32_bf16 v[4:7], v[148:151], v[230:233], v[4:7]
	v_mfma_f32_16x16x32_bf16 v[0:3], v[156:159], v[230:233], v[0:3]
	s_setprio 0
	s_setprio 1
	v_mfma_f32_16x16x32_bf16 v[94:97], v[160:163], v[188:191], v[94:97]
	v_mfma_f32_16x16x32_bf16 v[90:93], v[180:183], v[188:191], v[90:93]
	v_mfma_f32_16x16x32_bf16 v[86:89], v[160:163], v[196:199], v[86:89]
	v_mfma_f32_16x16x32_bf16 v[82:85], v[180:183], v[196:199], v[82:85]
	v_mfma_f32_16x16x32_bf16 v[78:81], v[160:163], v[204:207], v[78:81]
	v_mfma_f32_16x16x32_bf16 v[74:77], v[180:183], v[204:207], v[74:77]
	v_mfma_f32_16x16x32_bf16 v[70:73], v[160:163], v[212:215], v[70:73]
	v_mfma_f32_16x16x32_bf16 v[50:53], v[180:183], v[212:215], v[50:53]
	v_mfma_f32_16x16x32_bf16 v[94:97], v[176:179], v[192:195], v[94:97]
	v_mfma_f32_16x16x32_bf16 v[90:93], v[184:187], v[192:195], v[90:93]
	v_mfma_f32_16x16x32_bf16 v[86:89], v[176:179], v[200:203], v[86:89]
	v_mfma_f32_16x16x32_bf16 v[82:85], v[184:187], v[200:203], v[82:85]
	v_mfma_f32_16x16x32_bf16 v[78:81], v[176:179], v[208:211], v[78:81]
	v_mfma_f32_16x16x32_bf16 v[74:77], v[184:187], v[208:211], v[74:77]
	v_mfma_f32_16x16x32_bf16 v[70:73], v[176:179], v[230:233], v[70:73]
	v_mfma_f32_16x16x32_bf16 v[50:53], v[184:187], v[230:233], v[50:53]
	s_setprio 0
	s_barrier
	s_add_i32 s63, 0, 0x18000
	v_add_u32_e32 v16, s63, v166
	s_add_i32 s64, 0, 0x1c000
	ds_read_b128 v[144:147], v16
	ds_read_b128 v[148:151], v16 offset:1024
	ds_read_b128 v[152:155], v16 offset:2048
	ds_read_b128 v[156:159], v16 offset:3072
	v_add_u32_e32 v16, s64, v166
	ds_read_b128 v[160:163], v16
	ds_read_b128 v[176:179], v16 offset:1024
	ds_read_b128 v[180:183], v16 offset:2048
	ds_read_b128 v[184:187], v16 offset:3072
	s_add_u32 s28, s28, 0x80000
	s_addc_u32 s29, s29, 0
	s_mov_b32 m0, s39
	s_nop 0
	global_load_lds_dwordx4 v[172:173], off
	s_mov_b32 m0, s40
	s_nop 0
	global_load_lds_dwordx4 v[222:223], off
	s_mov_b32 m0, s41
	v_lshl_add_u64 v[224:225], s[28:29], 0, v[130:131]
	ds_read_b128 v[188:191], v167 offset:32768
	ds_read_b128 v[192:195], v167 offset:33792
	ds_read_b128 v[196:199], v167 offset:34816
	ds_read_b128 v[200:203], v167 offset:35840
	ds_read_b128 v[204:207], v167 offset:36864
	ds_read_b128 v[208:211], v167 offset:37888
	ds_read_b128 v[212:215], v167 offset:38912
	ds_read_b128 v[230:233], v167 offset:39936
	global_load_lds_dwordx4 v[224:225], off
	v_lshl_add_u64 v[224:225], s[28:29], 0, v[134:135]
	s_mov_b32 m0, s42
	s_nop 0
	global_load_lds_dwordx4 v[224:225], off
	s_waitcnt vmcnt(8)
	s_waitcnt lgkmcnt(0)
	s_barrier
	s_setprio 1
	s_waitcnt lgkmcnt(0)
	v_mfma_f32_16x16x32_bf16 v[66:69], v[144:147], v[188:191], v[66:69]
	v_mfma_f32_16x16x32_bf16 v[62:65], v[152:155], v[188:191], v[62:65]
	v_mfma_f32_16x16x32_bf16 v[58:61], v[144:147], v[196:199], v[58:61]
	v_mfma_f32_16x16x32_bf16 v[54:57], v[152:155], v[196:199], v[54:57]
	v_mfma_f32_16x16x32_bf16 v[46:49], v[144:147], v[204:207], v[46:49]
	v_mfma_f32_16x16x32_bf16 v[42:45], v[152:155], v[204:207], v[42:45]
	v_mfma_f32_16x16x32_bf16 v[38:41], v[144:147], v[212:215], v[38:41]
	v_mfma_f32_16x16x32_bf16 v[34:37], v[152:155], v[212:215], v[34:37]
	v_mfma_f32_16x16x32_bf16 v[66:69], v[148:151], v[192:195], v[66:69]
	v_mfma_f32_16x16x32_bf16 v[62:65], v[156:159], v[192:195], v[62:65]
	v_mfma_f32_16x16x32_bf16 v[58:61], v[148:151], v[200:203], v[58:61]
	v_mfma_f32_16x16x32_bf16 v[54:57], v[156:159], v[200:203], v[54:57]
	v_mfma_f32_16x16x32_bf16 v[46:49], v[148:151], v[208:211], v[46:49]
	v_mfma_f32_16x16x32_bf16 v[42:45], v[156:159], v[208:211], v[42:45]
	v_mfma_f32_16x16x32_bf16 v[38:41], v[148:151], v[230:233], v[38:41]
	v_mfma_f32_16x16x32_bf16 v[34:37], v[156:159], v[230:233], v[34:37]
	s_setprio 0
	s_setprio 1
	v_mfma_f32_16x16x32_bf16 v[126:129], v[160:163], v[188:191], v[126:129]
	v_mfma_f32_16x16x32_bf16 v[122:125], v[180:183], v[188:191], v[122:125]
	v_mfma_f32_16x16x32_bf16 v[118:121], v[160:163], v[196:199], v[118:121]
	v_mfma_f32_16x16x32_bf16 v[114:117], v[180:183], v[196:199], v[114:117]
	v_mfma_f32_16x16x32_bf16 v[110:113], v[160:163], v[204:207], v[110:113]
	v_mfma_f32_16x16x32_bf16 v[106:109], v[180:183], v[204:207], v[106:109]
	v_mfma_f32_16x16x32_bf16 v[102:105], v[160:163], v[212:215], v[102:105]
	v_mfma_f32_16x16x32_bf16 v[98:101], v[180:183], v[212:215], v[98:101]
	v_mfma_f32_16x16x32_bf16 v[126:129], v[176:179], v[192:195], v[126:129]
	v_mfma_f32_16x16x32_bf16 v[122:125], v[184:187], v[192:195], v[122:125]
	v_mfma_f32_16x16x32_bf16 v[118:121], v[176:179], v[200:203], v[118:121]
	v_mfma_f32_16x16x32_bf16 v[114:117], v[184:187], v[200:203], v[114:117]
	v_mfma_f32_16x16x32_bf16 v[110:113], v[176:179], v[208:211], v[110:113]
	v_mfma_f32_16x16x32_bf16 v[106:109], v[184:187], v[208:211], v[106:109]
	v_mfma_f32_16x16x32_bf16 v[102:105], v[176:179], v[230:233], v[102:105]
	v_mfma_f32_16x16x32_bf16 v[98:101], v[184:187], v[230:233], v[98:101]
	s_setprio 0
	s_barrier
	s_add_i32 s28, s63, s38
	v_lshl_add_u64 v[168:169], v[168:169], 0, s[56:57]
	s_mov_b32 m0, s28
	ds_read_b128 v[188:191], v167 offset:49152
	ds_read_b128 v[192:195], v167 offset:50176
	ds_read_b128 v[196:199], v167 offset:51200
	ds_read_b128 v[200:203], v167 offset:52224
	ds_read_b128 v[204:207], v167 offset:53248
	ds_read_b128 v[208:211], v167 offset:54272
	ds_read_b128 v[212:215], v167 offset:55296
	ds_read_b128 v[230:233], v167 offset:56320
	global_load_lds_dwordx4 v[168:169], off
	s_add_i32 m0, s28, 0x2000
	s_add_u32 s26, s26, 0x80080
	v_lshl_add_u64 v[168:169], v[170:171], 0, s[56:57]
	s_addc_u32 s27, s27, 0
	s_add_i32 s28, s64, s38
	global_load_lds_dwordx4 v[168:169], off
	v_lshl_add_u64 v[168:169], s[26:27], 0, v[132:133]
	s_mov_b32 m0, s28
	s_nop 0
	global_load_lds_dwordx4 v[168:169], off
	v_lshl_add_u64 v[168:169], s[26:27], 0, v[136:137]
	s_add_i32 m0, s28, 0x2000
	s_nop 0
	global_load_lds_dwordx4 v[168:169], off
	s_cmp_eq_u32 s62, 28
	s_cbranch_scc0 .Lbal_g1_notlast
	v_lshl_add_u64 v[168:169], v[172:173], 0, s[56:57]
	s_mov_b32 m0, s46
	s_nop 0
	global_load_lds_dwordx4 v[168:169], off
	v_lshl_add_u64 v[168:169], v[222:223], 0, s[56:57]
	s_mov_b32 m0, s47
	s_nop 0
	global_load_lds_dwordx4 v[168:169], off
	s_waitcnt vmcnt(8)
	s_branch .Lbal_g1_join

.Lbal_g1_join:
	s_waitcnt lgkmcnt(0)
	s_barrier
	s_setprio 1
	s_waitcnt lgkmcnt(0)
	v_mfma_f32_16x16x32_bf16 v[30:33], v[144:147], v[188:191], v[30:33]
	v_mfma_f32_16x16x32_bf16 v[26:29], v[152:155], v[188:191], v[26:29]
	v_mfma_f32_16x16x32_bf16 v[22:25], v[144:147], v[196:199], v[22:25]
	v_mfma_f32_16x16x32_bf16 v[18:21], v[152:155], v[196:199], v[18:21]
	v_mfma_f32_16x16x32_bf16 v[12:15], v[144:147], v[204:207], v[12:15]
	v_mfma_f32_16x16x32_bf16 v[8:11], v[152:155], v[204:207], v[8:11]
	v_mfma_f32_16x16x32_bf16 v[4:7], v[144:147], v[212:215], v[4:7]
	v_mfma_f32_16x16x32_bf16 v[0:3], v[152:155], v[212:215], v[0:3]
	v_mfma_f32_16x16x32_bf16 v[30:33], v[148:151], v[192:195], v[30:33]
	v_mfma_f32_16x16x32_bf16 v[26:29], v[156:159], v[192:195], v[26:29]
	v_mfma_f32_16x16x32_bf16 v[22:25], v[148:151], v[200:203], v[22:25]
	v_mfma_f32_16x16x32_bf16 v[18:21], v[156:159], v[200:203], v[18:21]
	v_mfma_f32_16x16x32_bf16 v[12:15], v[148:151], v[208:211], v[12:15]
	v_mfma_f32_16x16x32_bf16 v[8:11], v[156:159], v[208:211], v[8:11]
	v_mfma_f32_16x16x32_bf16 v[4:7], v[148:151], v[230:233], v[4:7]
	v_mfma_f32_16x16x32_bf16 v[0:3], v[156:159], v[230:233], v[0:3]
	s_setprio 0
	s_setprio 1
	v_mfma_f32_16x16x32_bf16 v[94:97], v[160:163], v[188:191], v[94:97]
	v_mfma_f32_16x16x32_bf16 v[90:93], v[180:183], v[188:191], v[90:93]
	v_mfma_f32_16x16x32_bf16 v[86:89], v[160:163], v[196:199], v[86:89]
	v_mfma_f32_16x16x32_bf16 v[82:85], v[180:183], v[196:199], v[82:85]
	v_mfma_f32_16x16x32_bf16 v[78:81], v[160:163], v[204:207], v[78:81]
	v_mfma_f32_16x16x32_bf16 v[74:77], v[180:183], v[204:207], v[74:77]
	v_mfma_f32_16x16x32_bf16 v[70:73], v[160:163], v[212:215], v[70:73]
	v_mfma_f32_16x16x32_bf16 v[50:53], v[180:183], v[212:215], v[50:53]
	v_mfma_f32_16x16x32_bf16 v[94:97], v[176:179], v[192:195], v[94:97]
	v_mfma_f32_16x16x32_bf16 v[90:93], v[184:187], v[192:195], v[90:93]
	v_mfma_f32_16x16x32_bf16 v[86:89], v[176:179], v[200:203], v[86:89]
	v_mfma_f32_16x16x32_bf16 v[82:85], v[184:187], v[200:203], v[82:85]
	v_mfma_f32_16x16x32_bf16 v[78:81], v[176:179], v[208:211], v[78:81]
	v_mfma_f32_16x16x32_bf16 v[74:77], v[184:187], v[208:211], v[74:77]
	v_mfma_f32_16x16x32_bf16 v[70:73], v[176:179], v[230:233], v[70:73]
	v_mfma_f32_16x16x32_bf16 v[50:53], v[184:187], v[230:233], v[50:53]
	s_setprio 0
	s_barrier
	s_add_i32 s62, s62, 2
	s_add_u32 s24, s24, 0x100
	s_addc_u32 s25, s25, 0
	s_add_u32 s60, s60, 0x100
	s_addc_u32 s61, s61, 0
	s_cmp_gt_u32 s62, 29
	s_cbranch_scc0 .LBB0_1018
	s_and_b64 vcc, exec, s[8:9]
	s_cbranch_vccz .LBB0_1021
	s_barrier
